# G6 + FoX epilogue xor-1 exchange by DPP instead of ds_bpermute + group-A pre-epilogue barrier moved into the epilogue (A starts its epilogue while B finishes its last MFMA segment) in P1 P5a P7 P8 P9
# speedup vs baseline: 1.0083x; 1.0031x over previous
.LBB0_200:
	ds_read_b128 v[148:151], v169
	ds_read_b128 v[152:155], v169 offset:1024
	ds_read_b128 v[156:159], v169 offset:2048
	ds_read_b128 v[160:163], v169 offset:3072
	ds_read_b128 v[174:177], v170
	ds_read_b128 v[178:181], v170 offset:1024
	ds_read_b128 v[182:185], v170 offset:2048
	ds_read_b128 v[186:189], v170 offset:3072
	s_add_u32 s26, s6, 0xfff00800
	s_addc_u32 s27, s7, -1
	s_cmp_eq_u32 s34, 60
	s_cselect_b32 s29, s17, s27
	s_cselect_b32 s28, s23, s26
	s_cselect_b32 s27, s15, s31
	s_cselect_b32 s26, s25, s30
	v_lshl_add_u64 v[190:191], s[6:7], 0, v[138:139]
	s_add_i32 m0, s41, 0xc000
	s_nop 0
	global_load_lds_dwordx4 v[190:191], off
	v_lshl_add_u64 v[190:191], s[6:7], 0, v[140:141]
	s_add_i32 m0, s41, 0xe000
	s_nop 0
	global_load_lds_dwordx4 v[190:191], off
	ds_read_b128 v[190:193], v171
	ds_read_b128 v[194:197], v171 offset:1024
	ds_read_b128 v[198:201], v171 offset:2048
	ds_read_b128 v[202:205], v171 offset:3072
	ds_read_b128 v[206:209], v171 offset:4096
	ds_read_b128 v[210:213], v171 offset:5120
	ds_read_b128 v[214:217], v171 offset:6144
	ds_read_b128 v[218:221], v171 offset:7168
	s_waitcnt vmcnt(8)
	s_waitcnt lgkmcnt(0)
	s_barrier
	s_waitcnt lgkmcnt(0)
	v_mfma_f32_16x16x32_bf16 v[124:127], v[148:151], v[190:193], v[124:127]
	v_mfma_f32_16x16x32_bf16 v[124:127], v[152:155], v[194:197], v[124:127]
	v_mfma_f32_16x16x32_bf16 v[120:123], v[160:163], v[194:197], v[120:123]
	v_mfma_f32_16x16x32_bf16 v[120:123], v[156:159], v[190:193], v[120:123]
	v_mfma_f32_16x16x32_bf16 v[60:63], v[174:177], v[190:193], v[60:63]
	v_mfma_f32_16x16x32_bf16 v[60:63], v[178:181], v[194:197], v[60:63]
	v_mfma_f32_16x16x32_bf16 v[56:59], v[186:189], v[194:197], v[56:59]
	v_mfma_f32_16x16x32_bf16 v[56:59], v[182:185], v[190:193], v[56:59]
	v_mfma_f32_16x16x32_bf16 v[48:51], v[182:185], v[198:201], v[48:51]
	v_mfma_f32_16x16x32_bf16 v[48:51], v[186:189], v[202:205], v[48:51]
	v_mfma_f32_16x16x32_bf16 v[52:55], v[178:181], v[202:205], v[52:55]
	v_mfma_f32_16x16x32_bf16 v[52:55], v[174:177], v[198:201], v[52:55]
	v_mfma_f32_16x16x32_bf16 v[112:115], v[156:159], v[198:201], v[112:115]
	v_mfma_f32_16x16x32_bf16 v[112:115], v[160:163], v[202:205], v[112:115]
	v_mfma_f32_16x16x32_bf16 v[116:119], v[152:155], v[202:205], v[116:119]
	v_mfma_f32_16x16x32_bf16 v[116:119], v[148:151], v[198:201], v[116:119]
	v_mfma_f32_16x16x32_bf16 v[108:111], v[148:151], v[206:209], v[108:111]
	v_mfma_f32_16x16x32_bf16 v[108:111], v[152:155], v[210:213], v[108:111]
	v_mfma_f32_16x16x32_bf16 v[104:107], v[160:163], v[210:213], v[104:107]
	v_mfma_f32_16x16x32_bf16 v[104:107], v[156:159], v[206:209], v[104:107]
	v_mfma_f32_16x16x32_bf16 v[44:47], v[174:177], v[206:209], v[44:47]
	v_mfma_f32_16x16x32_bf16 v[44:47], v[178:181], v[210:213], v[44:47]
	v_mfma_f32_16x16x32_bf16 v[40:43], v[186:189], v[210:213], v[40:43]
	v_mfma_f32_16x16x32_bf16 v[40:43], v[182:185], v[206:209], v[40:43]
	v_mfma_f32_16x16x32_bf16 v[32:35], v[182:185], v[214:217], v[32:35]
	v_mfma_f32_16x16x32_bf16 v[32:35], v[186:189], v[218:221], v[32:35]
	v_mfma_f32_16x16x32_bf16 v[36:39], v[178:181], v[218:221], v[36:39]
	v_mfma_f32_16x16x32_bf16 v[36:39], v[174:177], v[214:217], v[36:39]
	v_mfma_f32_16x16x32_bf16 v[96:99], v[156:159], v[214:217], v[96:99]
	v_mfma_f32_16x16x32_bf16 v[96:99], v[160:163], v[218:221], v[96:99]
	v_mfma_f32_16x16x32_bf16 v[100:103], v[152:155], v[218:221], v[100:103]
	v_mfma_f32_16x16x32_bf16 v[100:103], v[148:151], v[214:217], v[100:103]
	s_barrier
	s_add_i32 s35, s55, s36
	v_lshl_add_u64 v[222:223], s[26:27], 0, v[130:131]
	s_mov_b32 m0, s35
	v_lshl_add_u64 v[224:225], s[26:27], 0, v[134:135]
	global_load_lds_dwordx4 v[222:223], off
	s_add_i32 m0, s35, 0x2000
	s_add_u32 s58, s26, 0x100000
	s_addc_u32 s59, s27, 0
	s_add_i32 s35, s56, s36
	global_load_lds_dwordx4 v[224:225], off
	v_lshl_add_u64 v[190:191], s[58:59], 0, v[130:131]
	s_mov_b32 m0, s35
	v_lshl_add_u64 v[226:227], s[28:29], 0, v[128:129]
	global_load_lds_dwordx4 v[190:191], off
	v_lshl_add_u64 v[190:191], s[58:59], 0, v[134:135]
	s_add_i32 m0, s35, 0x2000
	v_lshl_add_u64 v[228:229], s[28:29], 0, v[132:133]
	global_load_lds_dwordx4 v[190:191], off
	s_mov_b32 m0, s41
	s_nop 0
	global_load_lds_dwordx4 v[226:227], off
	s_mov_b32 m0, s42
	s_nop 0
	global_load_lds_dwordx4 v[228:229], off
	ds_read_b128 v[190:193], v171 offset:16384
	ds_read_b128 v[194:197], v171 offset:17408
	ds_read_b128 v[198:201], v171 offset:18432
	ds_read_b128 v[202:205], v171 offset:19456
	ds_read_b128 v[206:209], v171 offset:20480
	ds_read_b128 v[210:213], v171 offset:21504
	ds_read_b128 v[214:217], v171 offset:22528
	ds_read_b128 v[218:221], v171 offset:23552
	s_waitcnt vmcnt(8)
	s_waitcnt lgkmcnt(0)
	s_barrier
	s_waitcnt lgkmcnt(0)
	v_mfma_f32_16x16x32_bf16 v[92:95], v[148:151], v[190:193], v[92:95]
	v_mfma_f32_16x16x32_bf16 v[92:95], v[152:155], v[194:197], v[92:95]
	v_mfma_f32_16x16x32_bf16 v[88:91], v[160:163], v[194:197], v[88:91]
	v_mfma_f32_16x16x32_bf16 v[88:91], v[156:159], v[190:193], v[88:91]
	v_mfma_f32_16x16x32_bf16 v[28:31], v[174:177], v[190:193], v[28:31]
	v_mfma_f32_16x16x32_bf16 v[28:31], v[178:181], v[194:197], v[28:31]
	v_mfma_f32_16x16x32_bf16 v[24:27], v[186:189], v[194:197], v[24:27]
	v_mfma_f32_16x16x32_bf16 v[24:27], v[182:185], v[190:193], v[24:27]
	v_mfma_f32_16x16x32_bf16 v[16:19], v[182:185], v[198:201], v[16:19]
	v_mfma_f32_16x16x32_bf16 v[16:19], v[186:189], v[202:205], v[16:19]
	v_mfma_f32_16x16x32_bf16 v[20:23], v[178:181], v[202:205], v[20:23]
	v_mfma_f32_16x16x32_bf16 v[20:23], v[174:177], v[198:201], v[20:23]
	v_mfma_f32_16x16x32_bf16 v[80:83], v[156:159], v[198:201], v[80:83]
	v_mfma_f32_16x16x32_bf16 v[80:83], v[160:163], v[202:205], v[80:83]
	v_mfma_f32_16x16x32_bf16 v[84:87], v[152:155], v[202:205], v[84:87]
	v_mfma_f32_16x16x32_bf16 v[84:87], v[148:151], v[198:201], v[84:87]
	v_mfma_f32_16x16x32_bf16 v[76:79], v[148:151], v[206:209], v[76:79]
	v_mfma_f32_16x16x32_bf16 v[76:79], v[152:155], v[210:213], v[76:79]
	v_mfma_f32_16x16x32_bf16 v[72:75], v[160:163], v[210:213], v[72:75]
	v_mfma_f32_16x16x32_bf16 v[72:75], v[156:159], v[206:209], v[72:75]
	v_mfma_f32_16x16x32_bf16 v[12:15], v[174:177], v[206:209], v[12:15]
	v_mfma_f32_16x16x32_bf16 v[12:15], v[178:181], v[210:213], v[12:15]
	v_mfma_f32_16x16x32_bf16 v[8:11], v[186:189], v[210:213], v[8:11]
	v_mfma_f32_16x16x32_bf16 v[8:11], v[182:185], v[206:209], v[8:11]
	v_mfma_f32_16x16x32_bf16 v[0:3], v[182:185], v[214:217], v[0:3]
	v_mfma_f32_16x16x32_bf16 v[0:3], v[186:189], v[218:221], v[0:3]
	v_mfma_f32_16x16x32_bf16 v[4:7], v[178:181], v[218:221], v[4:7]
	v_mfma_f32_16x16x32_bf16 v[4:7], v[174:177], v[214:217], v[4:7]
	v_mfma_f32_16x16x32_bf16 v[64:67], v[156:159], v[214:217], v[64:67]
	v_mfma_f32_16x16x32_bf16 v[64:67], v[160:163], v[218:221], v[64:67]
	v_mfma_f32_16x16x32_bf16 v[68:71], v[152:155], v[218:221], v[68:71]
	v_mfma_f32_16x16x32_bf16 v[68:71], v[148:151], v[214:217], v[68:71]
	s_barrier
	s_add_i32 s35, 0, 0x18000
	v_add_u32_e32 v136, s35, v165
	s_add_i32 s57, 0, 0x1c000
	ds_read_b128 v[148:151], v136
	ds_read_b128 v[152:155], v136 offset:1024
	ds_read_b128 v[156:159], v136 offset:2048
	ds_read_b128 v[160:163], v136 offset:3072
	v_add_u32_e32 v136, s57, v165
	ds_read_b128 v[174:177], v136
	ds_read_b128 v[178:181], v136 offset:1024
	ds_read_b128 v[182:185], v136 offset:2048
	ds_read_b128 v[186:189], v136 offset:3072
	s_add_u32 s28, s28, 0x100000
	s_addc_u32 s29, s29, 0
	s_mov_b32 m0, s43
	v_lshl_add_u64 v[190:191], s[28:29], 0, v[128:129]
	global_load_lds_dwordx4 v[190:191], off
	v_lshl_add_u64 v[190:191], s[28:29], 0, v[132:133]
	s_mov_b32 m0, s44
	s_nop 0
	global_load_lds_dwordx4 v[190:191], off
	ds_read_b128 v[190:193], v171 offset:32768
	ds_read_b128 v[194:197], v171 offset:33792
	ds_read_b128 v[198:201], v171 offset:34816
	ds_read_b128 v[202:205], v171 offset:35840
	ds_read_b128 v[206:209], v171 offset:36864
	ds_read_b128 v[210:213], v171 offset:37888
	ds_read_b128 v[214:217], v171 offset:38912
	ds_read_b128 v[218:221], v171 offset:39936
	s_waitcnt vmcnt(8)
	s_waitcnt lgkmcnt(0)
	s_barrier
	s_waitcnt lgkmcnt(0)
	v_mfma_f32_16x16x32_bf16 v[124:127], v[148:151], v[190:193], v[124:127]
	v_mfma_f32_16x16x32_bf16 v[124:127], v[152:155], v[194:197], v[124:127]
	v_mfma_f32_16x16x32_bf16 v[120:123], v[160:163], v[194:197], v[120:123]
	v_mfma_f32_16x16x32_bf16 v[120:123], v[156:159], v[190:193], v[120:123]
	v_mfma_f32_16x16x32_bf16 v[60:63], v[174:177], v[190:193], v[60:63]
	v_mfma_f32_16x16x32_bf16 v[60:63], v[178:181], v[194:197], v[60:63]
	v_mfma_f32_16x16x32_bf16 v[56:59], v[186:189], v[194:197], v[56:59]
	v_mfma_f32_16x16x32_bf16 v[56:59], v[182:185], v[190:193], v[56:59]
	v_mfma_f32_16x16x32_bf16 v[48:51], v[182:185], v[198:201], v[48:51]
	v_mfma_f32_16x16x32_bf16 v[48:51], v[186:189], v[202:205], v[48:51]
	v_mfma_f32_16x16x32_bf16 v[52:55], v[178:181], v[202:205], v[52:55]
	v_mfma_f32_16x16x32_bf16 v[52:55], v[174:177], v[198:201], v[52:55]
	v_mfma_f32_16x16x32_bf16 v[112:115], v[156:159], v[198:201], v[112:115]
	v_mfma_f32_16x16x32_bf16 v[112:115], v[160:163], v[202:205], v[112:115]
	v_mfma_f32_16x16x32_bf16 v[116:119], v[152:155], v[202:205], v[116:119]
	v_mfma_f32_16x16x32_bf16 v[116:119], v[148:151], v[198:201], v[116:119]
	v_mfma_f32_16x16x32_bf16 v[108:111], v[148:151], v[206:209], v[108:111]
	v_mfma_f32_16x16x32_bf16 v[108:111], v[152:155], v[210:213], v[108:111]
	v_mfma_f32_16x16x32_bf16 v[104:107], v[160:163], v[210:213], v[104:107]
	v_mfma_f32_16x16x32_bf16 v[104:107], v[156:159], v[206:209], v[104:107]
	v_mfma_f32_16x16x32_bf16 v[44:47], v[174:177], v[206:209], v[44:47]
	v_mfma_f32_16x16x32_bf16 v[44:47], v[178:181], v[210:213], v[44:47]
	v_mfma_f32_16x16x32_bf16 v[40:43], v[186:189], v[210:213], v[40:43]
	v_mfma_f32_16x16x32_bf16 v[40:43], v[182:185], v[206:209], v[40:43]
	v_mfma_f32_16x16x32_bf16 v[32:35], v[182:185], v[214:217], v[32:35]
	v_mfma_f32_16x16x32_bf16 v[32:35], v[186:189], v[218:221], v[32:35]
	v_mfma_f32_16x16x32_bf16 v[36:39], v[178:181], v[218:221], v[36:39]
	v_mfma_f32_16x16x32_bf16 v[36:39], v[174:177], v[214:217], v[36:39]
	v_mfma_f32_16x16x32_bf16 v[96:99], v[156:159], v[214:217], v[96:99]
	v_mfma_f32_16x16x32_bf16 v[96:99], v[160:163], v[218:221], v[96:99]
	v_mfma_f32_16x16x32_bf16 v[100:103], v[152:155], v[218:221], v[100:103]
	v_mfma_f32_16x16x32_bf16 v[100:103], v[148:151], v[214:217], v[100:103]
	s_barrier
	s_add_i32 s28, s35, s36
	v_lshl_add_u64 v[190:191], v[222:223], 0, s[12:13]
	s_mov_b32 m0, s28
	s_nop 0
	global_load_lds_dwordx4 v[190:191], off
	s_add_i32 m0, s28, 0x2000
	s_add_u32 s26, s26, 0x100800
	v_lshl_add_u64 v[190:191], v[224:225], 0, s[12:13]
	s_addc_u32 s27, s27, 0
	s_add_i32 s28, s57, s36
	global_load_lds_dwordx4 v[190:191], off
	v_lshl_add_u64 v[190:191], s[26:27], 0, v[130:131]
	s_mov_b32 m0, s28
	s_nop 0
	global_load_lds_dwordx4 v[190:191], off
	v_lshl_add_u64 v[190:191], s[26:27], 0, v[134:135]
	s_add_i32 m0, s28, 0x2000
	s_nop 0
	global_load_lds_dwordx4 v[190:191], off
	v_lshl_add_u64 v[190:191], v[226:227], 0, s[12:13]
	s_mov_b32 m0, s49
	s_nop 0
	global_load_lds_dwordx4 v[190:191], off
	v_lshl_add_u64 v[190:191], v[228:229], 0, s[12:13]
	s_mov_b32 m0, s50
	s_nop 0
	global_load_lds_dwordx4 v[190:191], off
	ds_read_b128 v[190:193], v171 offset:49152
	ds_read_b128 v[194:197], v171 offset:50176
	ds_read_b128 v[198:201], v171 offset:51200
	ds_read_b128 v[202:205], v171 offset:52224
	ds_read_b128 v[206:209], v171 offset:53248
	ds_read_b128 v[210:213], v171 offset:54272
	ds_read_b128 v[214:217], v171 offset:55296
	ds_read_b128 v[218:221], v171 offset:56320
	s_waitcnt vmcnt(8)
	s_waitcnt lgkmcnt(0)
	s_barrier
	s_waitcnt lgkmcnt(0)
	v_mfma_f32_16x16x32_bf16 v[92:95], v[148:151], v[190:193], v[92:95]
	v_mfma_f32_16x16x32_bf16 v[92:95], v[152:155], v[194:197], v[92:95]
	v_mfma_f32_16x16x32_bf16 v[88:91], v[160:163], v[194:197], v[88:91]
	v_mfma_f32_16x16x32_bf16 v[88:91], v[156:159], v[190:193], v[88:91]
	v_mfma_f32_16x16x32_bf16 v[28:31], v[174:177], v[190:193], v[28:31]
	v_mfma_f32_16x16x32_bf16 v[28:31], v[178:181], v[194:197], v[28:31]
	v_mfma_f32_16x16x32_bf16 v[24:27], v[186:189], v[194:197], v[24:27]
	v_mfma_f32_16x16x32_bf16 v[24:27], v[182:185], v[190:193], v[24:27]
	v_mfma_f32_16x16x32_bf16 v[16:19], v[182:185], v[198:201], v[16:19]
	v_mfma_f32_16x16x32_bf16 v[16:19], v[186:189], v[202:205], v[16:19]
	v_mfma_f32_16x16x32_bf16 v[20:23], v[178:181], v[202:205], v[20:23]
	v_mfma_f32_16x16x32_bf16 v[20:23], v[174:177], v[198:201], v[20:23]
	v_mfma_f32_16x16x32_bf16 v[80:83], v[156:159], v[198:201], v[80:83]
	v_mfma_f32_16x16x32_bf16 v[80:83], v[160:163], v[202:205], v[80:83]
	v_mfma_f32_16x16x32_bf16 v[84:87], v[152:155], v[202:205], v[84:87]
	v_mfma_f32_16x16x32_bf16 v[84:87], v[148:151], v[198:201], v[84:87]
	v_mfma_f32_16x16x32_bf16 v[76:79], v[148:151], v[206:209], v[76:79]
	v_mfma_f32_16x16x32_bf16 v[76:79], v[152:155], v[210:213], v[76:79]
	v_mfma_f32_16x16x32_bf16 v[72:75], v[160:163], v[210:213], v[72:75]
	v_mfma_f32_16x16x32_bf16 v[72:75], v[156:159], v[206:209], v[72:75]
	v_mfma_f32_16x16x32_bf16 v[12:15], v[174:177], v[206:209], v[12:15]
	v_mfma_f32_16x16x32_bf16 v[12:15], v[178:181], v[210:213], v[12:15]
	v_mfma_f32_16x16x32_bf16 v[8:11], v[186:189], v[210:213], v[8:11]
	v_mfma_f32_16x16x32_bf16 v[8:11], v[182:185], v[206:209], v[8:11]
	v_mfma_f32_16x16x32_bf16 v[0:3], v[182:185], v[214:217], v[0:3]
	v_mfma_f32_16x16x32_bf16 v[0:3], v[186:189], v[218:221], v[0:3]
	v_mfma_f32_16x16x32_bf16 v[4:7], v[178:181], v[218:221], v[4:7]
	v_mfma_f32_16x16x32_bf16 v[4:7], v[174:177], v[214:217], v[4:7]
	v_mfma_f32_16x16x32_bf16 v[64:67], v[156:159], v[214:217], v[64:67]
	v_mfma_f32_16x16x32_bf16 v[64:67], v[160:163], v[218:221], v[64:67]
	v_mfma_f32_16x16x32_bf16 v[68:71], v[152:155], v[218:221], v[68:71]
	v_mfma_f32_16x16x32_bf16 v[68:71], v[148:151], v[214:217], v[68:71]
	s_barrier
	s_add_i32 s34, s34, 2
	s_add_u32 s6, s6, 0x1000
	s_addc_u32 s7, s7, 0
	s_add_u32 s30, s30, 0x1000
	s_addc_u32 s31, s31, 0
	s_cmp_gt_u32 s34, 61
	s_cbranch_scc0 .LBB0_200

.LBB0_219:
	v_lshlrev_b32_e32 v136, 8, v154
	s_waitcnt vmcnt(0) lgkmcnt(0)
	v_pk_mul_f32 v[160:161], v[102:103], v[156:157] op_sel_hi:[1,0]
	v_pk_mul_f32 v[158:159], v[100:101], v[156:157] op_sel_hi:[1,0]
	v_pk_mul_f32 v[162:163], v[98:99], v[156:157] op_sel_hi:[1,0]
	v_and_b32_e32 v136, 0xf7f00, v136
	v_pk_mul_f32 v[174:175], v[96:97], v[156:157] op_sel_hi:[1,0]
	v_cvt_pk_bf16_f32 v158, v158, v159
	v_cvt_pk_bf16_f32 v159, v160, v161
	v_mov_b32_e32 v147, v137
	v_cvt_pk_bf16_f32 v160, v174, v175
	v_cvt_pk_bf16_f32 v161, v162, v163
	v_lshl_add_u64 v[162:163], s[28:29], 0, v[136:137]
	v_lshl_add_u64 v[162:163], v[162:163], 0, v[146:147]
	global_store_dwordx4 v[162:163], v[158:161], off
	s_and_b64 vcc, exec, s[0:1]
	s_cbranch_vccz .Lepibar_P1
	s_barrier
.Lepibar_P1:
	v_pk_mul_f32 v[162:163], v[34:35], v[156:157] op_sel_hi:[1,0]
	v_pk_mul_f32 v[174:175], v[32:33], v[156:157] op_sel_hi:[1,0]
	v_pk_mul_f32 v[160:161], v[36:37], v[156:157] op_sel_hi:[1,0]
	v_pk_mul_f32 v[158:159], v[38:39], v[156:157] op_sel_hi:[1,0]
	v_cvt_pk_bf16_f32 v156, v160, v161
	v_lshl_add_u64 v[160:161], s[30:31], 0, v[136:137]
	v_lshl_add_u64 v[160:161], v[160:161], 0, v[146:147]
	v_cvt_pk_bf16_f32 v157, v158, v159
	v_cvt_pk_bf16_f32 v158, v174, v175
	v_cvt_pk_bf16_f32 v159, v162, v163
	global_store_dwordx4 v[160:161], v[156:159], off
	s_and_b64 vcc, exec, s[6:7]
	s_mov_b64 s[34:35], -1
	v_or_b32_e32 v156, 0x80, v148
	s_cbranch_vccnz .LBB0_221
	v_ashrrev_i32_e32 v157, 31, v156
	v_lshl_add_u64 v[158:159], v[156:157], 2, s[10:11]
	global_load_dword v158, v[158:159], off
	s_mov_b64 s[34:35], 0

.LBB0_604:
	s_or_b64 exec, exec, s[8:9]
	s_and_saveexec_b64 s[0:1], s[2:3]
	v_lshl_add_u32 v0, v190, 2, s66
	ds_write_b32 v0, v120
	s_or_b64 exec, exec, s[0:1]
	s_waitcnt lgkmcnt(0)
	ds_read_b128 v[104:107], v194
	ds_read_b128 v[100:103], v194 offset:32
	ds_read_b128 v[96:99], v194 offset:64
	ds_read_b128 v[92:95], v194 offset:96
	v_readlane_b32 s0, v255, 53
	s_add_u32 s0, s79, s0
	v_and_b32_e32 v0, 1, v189
	s_waitcnt lgkmcnt(3)
	v_rcp_f32_e32 v104, v104
	s_addc_u32 s1, s76, 0
	v_cmp_eq_u32_e64 s[2:3], 0, v0
	v_lshlrev_b32_e32 v0, 1, v190
	v_mul_f32_e32 v64, v64, v104
	s_nop 1
	v_mov_b32_dpp v108, v64 quad_perm:[1,0,3,2] row_mask:0xf bank_mask:0xf
	v_mov_b32_e32 v1, v2
	v_lshl_add_u64 v[0:1], s[0:1], 0, v[0:1]
	v_lshlrev_b32_e32 v110, 15, v191
	v_mov_b32_e32 v111, v2
	v_lshl_add_u64 v[0:1], v[0:1], 0, v[110:111]
	s_and_saveexec_b64 s[0:1], s[2:3]
	s_cbranch_execz .LBB0_608
	s_waitcnt lgkmcnt(0)
	v_cvt_pk_bf16_f32 v64, v64, v108
	global_store_dword v[0:1], v64, off
.LBB0_608:
	s_or_b64 exec, exec, s[0:1]
	v_mul_f32_e32 v48, v48, v104
	s_nop 1
	v_mov_b32_dpp v64, v48 quad_perm:[1,0,3,2] row_mask:0xf bank_mask:0xf
	s_and_saveexec_b64 s[0:1], s[2:3]
	s_cbranch_execz .LBB0_610
	s_waitcnt lgkmcnt(0)
	v_cvt_pk_bf16_f32 v48, v48, v64
	global_store_dword v[0:1], v48, off offset:64
.LBB0_610:
	s_or_b64 exec, exec, s[0:1]
	v_mul_f32_e32 v32, v32, v104
	s_nop 1
	v_mov_b32_dpp v48, v32 quad_perm:[1,0,3,2] row_mask:0xf bank_mask:0xf
	s_and_saveexec_b64 s[0:1], s[2:3]
	s_cbranch_execz .LBB0_612
	s_waitcnt lgkmcnt(0)
	v_cvt_pk_bf16_f32 v32, v32, v48
	global_store_dword v[0:1], v32, off offset:128
.LBB0_612:
	s_or_b64 exec, exec, s[0:1]
	v_mul_f32_e32 v16, v16, v104
	s_nop 1
	v_mov_b32_dpp v32, v16 quad_perm:[1,0,3,2] row_mask:0xf bank_mask:0xf
	s_and_saveexec_b64 s[0:1], s[2:3]
	s_cbranch_execz .LBB0_614
	s_waitcnt lgkmcnt(0)
	v_cvt_pk_bf16_f32 v16, v16, v32
	global_store_dword v[0:1], v16, off offset:192
.LBB0_614:
	s_or_b64 exec, exec, s[0:1]
	v_rcp_f32_e32 v16, v105
	s_waitcnt lgkmcnt(0)
	v_mul_f32_e32 v32, v65, v16
	s_nop 1
	v_mov_b32_dpp v48, v32 quad_perm:[1,0,3,2] row_mask:0xf bank_mask:0xf
	s_and_saveexec_b64 s[0:1], s[2:3]
	s_cbranch_execz .LBB0_616
	v_add_co_u32_e32 v64, vcc, 0x2000, v0
	s_waitcnt lgkmcnt(0)
	v_cvt_pk_bf16_f32 v32, v32, v48
	s_nop 0
	v_addc_co_u32_e32 v65, vcc, 0, v1, vcc
	global_store_dword v[64:65], v32, off
.LBB0_616:
	s_or_b64 exec, exec, s[0:1]
	v_mul_f32_e32 v32, v49, v16
	s_waitcnt lgkmcnt(0)
	s_nop 1
	v_mov_b32_dpp v48, v32 quad_perm:[1,0,3,2] row_mask:0xf bank_mask:0xf
	s_and_saveexec_b64 s[0:1], s[2:3]
	s_cbranch_execz .LBB0_618
	s_waitcnt lgkmcnt(0)
	v_cvt_pk_bf16_f32 v32, v32, v48
	v_add_co_u32_e32 v48, vcc, 0x2000, v0
	s_nop 1
	v_addc_co_u32_e32 v49, vcc, 0, v1, vcc
	global_store_dword v[48:49], v32, off offset:64
.LBB0_618:
	s_or_b64 exec, exec, s[0:1]
	v_mul_f32_e32 v32, v33, v16
	s_nop 1
	v_mov_b32_dpp v33, v32 quad_perm:[1,0,3,2] row_mask:0xf bank_mask:0xf
	s_and_saveexec_b64 s[0:1], s[2:3]
	s_cbranch_execz .LBB0_620
	s_waitcnt lgkmcnt(0)
	v_cvt_pk_bf16_f32 v48, v32, v33
	v_add_co_u32_e32 v32, vcc, 0x2000, v0
	s_nop 1
	v_addc_co_u32_e32 v33, vcc, 0, v1, vcc
	global_store_dword v[32:33], v48, off offset:128
.LBB0_620:
	s_or_b64 exec, exec, s[0:1]
	v_mul_f32_e32 v16, v17, v16
	s_nop 1
	v_mov_b32_dpp v17, v16 quad_perm:[1,0,3,2] row_mask:0xf bank_mask:0xf
	s_and_saveexec_b64 s[0:1], s[2:3]
	s_cbranch_execz .LBB0_622
	s_waitcnt lgkmcnt(0)
	v_cvt_pk_bf16_f32 v32, v16, v17
	v_add_co_u32_e32 v16, vcc, 0x2000, v0
	s_nop 1
	v_addc_co_u32_e32 v17, vcc, 0, v1, vcc
	global_store_dword v[16:17], v32, off offset:192
.LBB0_622:
	s_or_b64 exec, exec, s[0:1]
	v_rcp_f32_e32 v16, v106
	s_waitcnt lgkmcnt(0)
	v_mul_f32_e32 v17, v66, v16
	s_nop 1
	v_mov_b32_dpp v32, v17 quad_perm:[1,0,3,2] row_mask:0xf bank_mask:0xf
	s_and_saveexec_b64 s[0:1], s[2:3]
	s_cbranch_execz .LBB0_624
	s_waitcnt lgkmcnt(0)
	v_cvt_pk_bf16_f32 v17, v17, v32
	v_add_co_u32_e32 v32, vcc, 0x4000, v0
	s_nop 1
	v_addc_co_u32_e32 v33, vcc, 0, v1, vcc
	global_store_dword v[32:33], v17, off
.LBB0_624:
	s_or_b64 exec, exec, s[0:1]
	v_mul_f32_e32 v17, v50, v16
	s_waitcnt lgkmcnt(0)
	s_nop 1
	v_mov_b32_dpp v32, v17 quad_perm:[1,0,3,2] row_mask:0xf bank_mask:0xf
	s_and_saveexec_b64 s[0:1], s[2:3]
	s_cbranch_execz .LBB0_626
	s_waitcnt lgkmcnt(0)
	v_cvt_pk_bf16_f32 v17, v17, v32
	v_add_co_u32_e32 v32, vcc, 0x4000, v0
	s_nop 1
	v_addc_co_u32_e32 v33, vcc, 0, v1, vcc
	global_store_dword v[32:33], v17, off offset:64
.LBB0_626:
	s_or_b64 exec, exec, s[0:1]
	v_mul_f32_e32 v17, v34, v16
	s_waitcnt lgkmcnt(0)
	s_nop 1
	v_mov_b32_dpp v32, v17 quad_perm:[1,0,3,2] row_mask:0xf bank_mask:0xf
	s_and_saveexec_b64 s[0:1], s[2:3]
	s_cbranch_execz .LBB0_628
	s_waitcnt lgkmcnt(0)
	v_cvt_pk_bf16_f32 v17, v17, v32
	v_add_co_u32_e32 v32, vcc, 0x4000, v0
	s_nop 1
	v_addc_co_u32_e32 v33, vcc, 0, v1, vcc
	global_store_dword v[32:33], v17, off offset:128
.LBB0_628:
	s_or_b64 exec, exec, s[0:1]
	v_mul_f32_e32 v16, v18, v16
	s_nop 1
	v_mov_b32_dpp v17, v16 quad_perm:[1,0,3,2] row_mask:0xf bank_mask:0xf
	s_and_saveexec_b64 s[0:1], s[2:3]
	s_cbranch_execz .LBB0_630
	s_waitcnt lgkmcnt(0)
	v_cvt_pk_bf16_f32 v18, v16, v17
	v_add_co_u32_e32 v16, vcc, 0x4000, v0
	s_nop 1
	v_addc_co_u32_e32 v17, vcc, 0, v1, vcc
	global_store_dword v[16:17], v18, off offset:192
.LBB0_630:
	s_or_b64 exec, exec, s[0:1]
	v_rcp_f32_e32 v16, v107
	s_waitcnt lgkmcnt(0)
	v_mul_f32_e32 v17, v67, v16
	s_nop 1
	v_mov_b32_dpp v18, v17 quad_perm:[1,0,3,2] row_mask:0xf bank_mask:0xf
	s_and_saveexec_b64 s[0:1], s[2:3]
	s_cbranch_execz .LBB0_632
	v_add_co_u32_e32 v32, vcc, 0x6000, v0
	s_waitcnt lgkmcnt(0)
	v_cvt_pk_bf16_f32 v17, v17, v18
	s_nop 0
	v_addc_co_u32_e32 v33, vcc, 0, v1, vcc
	global_store_dword v[32:33], v17, off
.LBB0_632:
	s_or_b64 exec, exec, s[0:1]
	v_mul_f32_e32 v17, v51, v16
	s_waitcnt lgkmcnt(0)
	s_nop 1
	v_mov_b32_dpp v18, v17 quad_perm:[1,0,3,2] row_mask:0xf bank_mask:0xf
	s_and_saveexec_b64 s[0:1], s[2:3]
	s_cbranch_execz .LBB0_634
	v_add_co_u32_e32 v32, vcc, 0x6000, v0
	s_waitcnt lgkmcnt(0)
	v_cvt_pk_bf16_f32 v17, v17, v18
	s_nop 0
	v_addc_co_u32_e32 v33, vcc, 0, v1, vcc
	global_store_dword v[32:33], v17, off offset:64
.LBB0_634:
	s_or_b64 exec, exec, s[0:1]
	v_mul_f32_e32 v17, v35, v16
	s_waitcnt lgkmcnt(0)
	s_nop 1
	v_mov_b32_dpp v18, v17 quad_perm:[1,0,3,2] row_mask:0xf bank_mask:0xf
	s_and_saveexec_b64 s[0:1], s[2:3]
	s_cbranch_execz .LBB0_636
	v_add_co_u32_e32 v32, vcc, 0x6000, v0
	s_waitcnt lgkmcnt(0)
	v_cvt_pk_bf16_f32 v17, v17, v18
	s_nop 0
	v_addc_co_u32_e32 v33, vcc, 0, v1, vcc
	global_store_dword v[32:33], v17, off offset:128
.LBB0_636:
	s_or_b64 exec, exec, s[0:1]
	v_mul_f32_e32 v16, v19, v16
	s_nop 1
	v_mov_b32_dpp v17, v16 quad_perm:[1,0,3,2] row_mask:0xf bank_mask:0xf
	s_and_saveexec_b64 s[0:1], s[2:3]
	s_cbranch_execz .LBB0_638
	s_waitcnt lgkmcnt(0)
	v_cvt_pk_bf16_f32 v18, v16, v17
	v_add_co_u32_e32 v16, vcc, 0x6000, v0
	s_nop 1
	v_addc_co_u32_e32 v17, vcc, 0, v1, vcc
	global_store_dword v[16:17], v18, off offset:192
.LBB0_638:
	s_or_b64 exec, exec, s[0:1]
	v_rcp_f32_e32 v16, v100
	s_waitcnt lgkmcnt(0)
	v_mul_f32_e32 v17, v68, v16
	s_nop 1
	v_mov_b32_dpp v18, v17 quad_perm:[1,0,3,2] row_mask:0xf bank_mask:0xf
	s_and_saveexec_b64 s[0:1], s[2:3]
	s_cbranch_execz .LBB0_640
	s_waitcnt lgkmcnt(0)
	v_cvt_pk_bf16_f32 v17, v17, v18
	v_add_co_u32_e32 v18, vcc, 0x10000, v0
	s_nop 1
	v_addc_co_u32_e32 v19, vcc, 0, v1, vcc
	global_store_dword v[18:19], v17, off
.LBB0_640:
	s_or_b64 exec, exec, s[0:1]
	v_mul_f32_e32 v17, v52, v16
	s_waitcnt lgkmcnt(0)
	s_nop 1
	v_mov_b32_dpp v18, v17 quad_perm:[1,0,3,2] row_mask:0xf bank_mask:0xf
	s_and_saveexec_b64 s[0:1], s[2:3]
	s_cbranch_execz .LBB0_642
	s_waitcnt lgkmcnt(0)
	v_cvt_pk_bf16_f32 v17, v17, v18
	v_add_co_u32_e32 v18, vcc, 0x10000, v0
	s_nop 1
	v_addc_co_u32_e32 v19, vcc, 0, v1, vcc
	global_store_dword v[18:19], v17, off offset:64
.LBB0_642:
	s_or_b64 exec, exec, s[0:1]
	v_mul_f32_e32 v17, v36, v16
	s_waitcnt lgkmcnt(0)
	s_nop 1
	v_mov_b32_dpp v18, v17 quad_perm:[1,0,3,2] row_mask:0xf bank_mask:0xf
	s_and_saveexec_b64 s[0:1], s[2:3]
	s_cbranch_execz .LBB0_644
	s_waitcnt lgkmcnt(0)
	v_cvt_pk_bf16_f32 v17, v17, v18
	v_add_co_u32_e32 v18, vcc, 0x10000, v0
	s_nop 1
	v_addc_co_u32_e32 v19, vcc, 0, v1, vcc
	global_store_dword v[18:19], v17, off offset:128
.LBB0_644:
	s_or_b64 exec, exec, s[0:1]
	v_mul_f32_e32 v16, v20, v16
	s_nop 1
	v_mov_b32_dpp v17, v16 quad_perm:[1,0,3,2] row_mask:0xf bank_mask:0xf
	s_and_saveexec_b64 s[0:1], s[2:3]
	s_cbranch_execz .LBB0_646
	s_waitcnt lgkmcnt(0)
	v_cvt_pk_bf16_f32 v18, v16, v17
	v_add_co_u32_e32 v16, vcc, 0x10000, v0
	s_nop 1
	v_addc_co_u32_e32 v17, vcc, 0, v1, vcc
	global_store_dword v[16:17], v18, off offset:192
.LBB0_646:
	s_or_b64 exec, exec, s[0:1]
	v_rcp_f32_e32 v16, v101
	s_waitcnt lgkmcnt(0)
	v_mul_f32_e32 v17, v69, v16
	s_nop 1
	v_mov_b32_dpp v18, v17 quad_perm:[1,0,3,2] row_mask:0xf bank_mask:0xf
	s_and_saveexec_b64 s[0:1], s[2:3]
	s_cbranch_execz .LBB0_648
	s_waitcnt lgkmcnt(0)
	v_cvt_pk_bf16_f32 v17, v17, v18
	v_add_co_u32_e32 v18, vcc, 0x12000, v0
	s_nop 1
	v_addc_co_u32_e32 v19, vcc, 0, v1, vcc
	global_store_dword v[18:19], v17, off
.LBB0_648:
	s_or_b64 exec, exec, s[0:1]
	v_mul_f32_e32 v17, v53, v16
	s_waitcnt lgkmcnt(0)
	s_nop 1
	v_mov_b32_dpp v18, v17 quad_perm:[1,0,3,2] row_mask:0xf bank_mask:0xf
	s_and_saveexec_b64 s[0:1], s[2:3]
	s_cbranch_execz .LBB0_650
	s_waitcnt lgkmcnt(0)
	v_cvt_pk_bf16_f32 v17, v17, v18
	v_add_co_u32_e32 v18, vcc, 0x12000, v0
	s_nop 1
	v_addc_co_u32_e32 v19, vcc, 0, v1, vcc
	global_store_dword v[18:19], v17, off offset:64
.LBB0_650:
	s_or_b64 exec, exec, s[0:1]
	v_mul_f32_e32 v17, v37, v16
	s_waitcnt lgkmcnt(0)
	s_nop 1
	v_mov_b32_dpp v18, v17 quad_perm:[1,0,3,2] row_mask:0xf bank_mask:0xf
	s_and_saveexec_b64 s[0:1], s[2:3]
	s_cbranch_execz .LBB0_652
	s_waitcnt lgkmcnt(0)
	v_cvt_pk_bf16_f32 v17, v17, v18
	v_add_co_u32_e32 v18, vcc, 0x12000, v0
	s_nop 1
	v_addc_co_u32_e32 v19, vcc, 0, v1, vcc
	global_store_dword v[18:19], v17, off offset:128
.LBB0_652:
	s_or_b64 exec, exec, s[0:1]
	v_mul_f32_e32 v16, v21, v16
	s_nop 1
	v_mov_b32_dpp v17, v16 quad_perm:[1,0,3,2] row_mask:0xf bank_mask:0xf
	s_and_saveexec_b64 s[0:1], s[2:3]
	s_cbranch_execz .LBB0_654
	s_waitcnt lgkmcnt(0)
	v_cvt_pk_bf16_f32 v18, v16, v17
	v_add_co_u32_e32 v16, vcc, 0x12000, v0
	s_nop 1
	v_addc_co_u32_e32 v17, vcc, 0, v1, vcc
	global_store_dword v[16:17], v18, off offset:192
.LBB0_654:
	s_or_b64 exec, exec, s[0:1]
	v_rcp_f32_e32 v16, v102
	s_waitcnt lgkmcnt(0)
	v_mul_f32_e32 v17, v70, v16
	s_nop 1
	v_mov_b32_dpp v18, v17 quad_perm:[1,0,3,2] row_mask:0xf bank_mask:0xf
	s_and_saveexec_b64 s[0:1], s[2:3]
	s_cbranch_execz .LBB0_656
	s_waitcnt lgkmcnt(0)
	v_cvt_pk_bf16_f32 v17, v17, v18
	v_add_co_u32_e32 v18, vcc, 0x14000, v0
	s_nop 1
	v_addc_co_u32_e32 v19, vcc, 0, v1, vcc
	global_store_dword v[18:19], v17, off
.LBB0_656:
	s_or_b64 exec, exec, s[0:1]
	v_mul_f32_e32 v17, v54, v16
	s_waitcnt lgkmcnt(0)
	s_nop 1
	v_mov_b32_dpp v18, v17 quad_perm:[1,0,3,2] row_mask:0xf bank_mask:0xf
	s_and_saveexec_b64 s[0:1], s[2:3]
	s_cbranch_execz .LBB0_658
	s_waitcnt lgkmcnt(0)
	v_cvt_pk_bf16_f32 v17, v17, v18
	v_add_co_u32_e32 v18, vcc, 0x14000, v0
	s_nop 1
	v_addc_co_u32_e32 v19, vcc, 0, v1, vcc
	global_store_dword v[18:19], v17, off offset:64
.LBB0_658:
	s_or_b64 exec, exec, s[0:1]
	v_mul_f32_e32 v17, v38, v16
	s_waitcnt lgkmcnt(0)
	s_nop 1
	v_mov_b32_dpp v18, v17 quad_perm:[1,0,3,2] row_mask:0xf bank_mask:0xf
	s_and_saveexec_b64 s[0:1], s[2:3]
	s_cbranch_execz .LBB0_660
	s_waitcnt lgkmcnt(0)
	v_cvt_pk_bf16_f32 v17, v17, v18
	v_add_co_u32_e32 v18, vcc, 0x14000, v0
	s_nop 1
	v_addc_co_u32_e32 v19, vcc, 0, v1, vcc
	global_store_dword v[18:19], v17, off offset:128
.LBB0_660:
	s_or_b64 exec, exec, s[0:1]
	v_mul_f32_e32 v16, v22, v16
	s_nop 1
	v_mov_b32_dpp v17, v16 quad_perm:[1,0,3,2] row_mask:0xf bank_mask:0xf
	s_and_saveexec_b64 s[0:1], s[2:3]
	s_cbranch_execz .LBB0_662
	s_waitcnt lgkmcnt(0)
	v_cvt_pk_bf16_f32 v18, v16, v17
	v_add_co_u32_e32 v16, vcc, 0x14000, v0
	s_nop 1
	v_addc_co_u32_e32 v17, vcc, 0, v1, vcc
	global_store_dword v[16:17], v18, off offset:192
.LBB0_662:
	s_or_b64 exec, exec, s[0:1]
	v_rcp_f32_e32 v16, v103
	s_waitcnt lgkmcnt(0)
	v_mul_f32_e32 v17, v71, v16
	s_nop 1
	v_mov_b32_dpp v18, v17 quad_perm:[1,0,3,2] row_mask:0xf bank_mask:0xf
	s_and_saveexec_b64 s[0:1], s[2:3]
	s_cbranch_execz .LBB0_664
	s_waitcnt lgkmcnt(0)
	v_cvt_pk_bf16_f32 v17, v17, v18
	v_add_co_u32_e32 v18, vcc, 0x16000, v0
	s_nop 1
	v_addc_co_u32_e32 v19, vcc, 0, v1, vcc
	global_store_dword v[18:19], v17, off
.LBB0_664:
	s_or_b64 exec, exec, s[0:1]
	v_mul_f32_e32 v17, v55, v16
	s_waitcnt lgkmcnt(0)
	s_nop 1
	v_mov_b32_dpp v18, v17 quad_perm:[1,0,3,2] row_mask:0xf bank_mask:0xf
	s_and_saveexec_b64 s[0:1], s[2:3]
	s_cbranch_execz .LBB0_666
	s_waitcnt lgkmcnt(0)
	v_cvt_pk_bf16_f32 v17, v17, v18
	v_add_co_u32_e32 v18, vcc, 0x16000, v0
	s_nop 1
	v_addc_co_u32_e32 v19, vcc, 0, v1, vcc
	global_store_dword v[18:19], v17, off offset:64
.LBB0_666:
	s_or_b64 exec, exec, s[0:1]
	v_mul_f32_e32 v17, v39, v16
	s_waitcnt lgkmcnt(0)
	s_nop 1
	v_mov_b32_dpp v18, v17 quad_perm:[1,0,3,2] row_mask:0xf bank_mask:0xf
	s_and_saveexec_b64 s[0:1], s[2:3]
	s_cbranch_execz .LBB0_668
	s_waitcnt lgkmcnt(0)
	v_cvt_pk_bf16_f32 v17, v17, v18
	v_add_co_u32_e32 v18, vcc, 0x16000, v0
	s_nop 1
	v_addc_co_u32_e32 v19, vcc, 0, v1, vcc
	global_store_dword v[18:19], v17, off offset:128
.LBB0_668:
	s_or_b64 exec, exec, s[0:1]
	v_mul_f32_e32 v16, v23, v16
	s_nop 1
	v_mov_b32_dpp v17, v16 quad_perm:[1,0,3,2] row_mask:0xf bank_mask:0xf
	s_and_saveexec_b64 s[0:1], s[2:3]
	s_cbranch_execz .LBB0_670
	s_waitcnt lgkmcnt(0)
	v_cvt_pk_bf16_f32 v18, v16, v17
	v_add_co_u32_e32 v16, vcc, 0x16000, v0
	s_nop 1
	v_addc_co_u32_e32 v17, vcc, 0, v1, vcc
	global_store_dword v[16:17], v18, off offset:192
.LBB0_670:
	s_or_b64 exec, exec, s[0:1]
	v_rcp_f32_e32 v16, v96
	s_waitcnt lgkmcnt(0)
	v_mul_f32_e32 v17, v72, v16
	s_nop 1
	v_mov_b32_dpp v18, v17 quad_perm:[1,0,3,2] row_mask:0xf bank_mask:0xf
	s_and_saveexec_b64 s[0:1], s[2:3]
	s_cbranch_execz .LBB0_672
	s_waitcnt lgkmcnt(0)
	v_cvt_pk_bf16_f32 v17, v17, v18
	v_add_co_u32_e32 v18, vcc, 0x20000, v0
	s_nop 1
	v_addc_co_u32_e32 v19, vcc, 0, v1, vcc
	global_store_dword v[18:19], v17, off
.LBB0_672:
	s_or_b64 exec, exec, s[0:1]
	v_mul_f32_e32 v17, v56, v16
	s_waitcnt lgkmcnt(0)
	s_nop 1
	v_mov_b32_dpp v18, v17 quad_perm:[1,0,3,2] row_mask:0xf bank_mask:0xf
	s_and_saveexec_b64 s[0:1], s[2:3]
	s_cbranch_execz .LBB0_674
	s_waitcnt lgkmcnt(0)
	v_cvt_pk_bf16_f32 v17, v17, v18
	v_add_co_u32_e32 v18, vcc, 0x20000, v0
	s_nop 1
	v_addc_co_u32_e32 v19, vcc, 0, v1, vcc
	global_store_dword v[18:19], v17, off offset:64
.LBB0_674:
	s_or_b64 exec, exec, s[0:1]
	v_mul_f32_e32 v17, v40, v16
	s_waitcnt lgkmcnt(0)
	s_nop 1
	v_mov_b32_dpp v18, v17 quad_perm:[1,0,3,2] row_mask:0xf bank_mask:0xf
	s_and_saveexec_b64 s[0:1], s[2:3]
	s_cbranch_execz .LBB0_676
	s_waitcnt lgkmcnt(0)
	v_cvt_pk_bf16_f32 v17, v17, v18
	v_add_co_u32_e32 v18, vcc, 0x20000, v0
	s_nop 1
	v_addc_co_u32_e32 v19, vcc, 0, v1, vcc
	global_store_dword v[18:19], v17, off offset:128
.LBB0_676:
	s_or_b64 exec, exec, s[0:1]
	v_mul_f32_e32 v16, v24, v16
	s_nop 1
	v_mov_b32_dpp v17, v16 quad_perm:[1,0,3,2] row_mask:0xf bank_mask:0xf
	s_and_saveexec_b64 s[0:1], s[2:3]
	s_cbranch_execz .LBB0_678
	s_waitcnt lgkmcnt(0)
	v_cvt_pk_bf16_f32 v18, v16, v17
	v_add_co_u32_e32 v16, vcc, 0x20000, v0
	s_nop 1
	v_addc_co_u32_e32 v17, vcc, 0, v1, vcc
	global_store_dword v[16:17], v18, off offset:192
.LBB0_678:
	s_or_b64 exec, exec, s[0:1]
	v_rcp_f32_e32 v16, v97
	s_waitcnt lgkmcnt(0)
	v_mul_f32_e32 v17, v73, v16
	s_nop 1
	v_mov_b32_dpp v18, v17 quad_perm:[1,0,3,2] row_mask:0xf bank_mask:0xf
	s_and_saveexec_b64 s[0:1], s[2:3]
	s_cbranch_execz .LBB0_680
	s_waitcnt lgkmcnt(0)
	v_cvt_pk_bf16_f32 v17, v17, v18
	v_add_co_u32_e32 v18, vcc, 0x22000, v0
	s_nop 1
	v_addc_co_u32_e32 v19, vcc, 0, v1, vcc
	global_store_dword v[18:19], v17, off
.LBB0_680:
	s_or_b64 exec, exec, s[0:1]
	v_mul_f32_e32 v17, v57, v16
	s_waitcnt lgkmcnt(0)
	s_nop 1
	v_mov_b32_dpp v18, v17 quad_perm:[1,0,3,2] row_mask:0xf bank_mask:0xf
	s_and_saveexec_b64 s[0:1], s[2:3]
	s_cbranch_execz .LBB0_682
	s_waitcnt lgkmcnt(0)
	v_cvt_pk_bf16_f32 v17, v17, v18
	v_add_co_u32_e32 v18, vcc, 0x22000, v0
	s_nop 1
	v_addc_co_u32_e32 v19, vcc, 0, v1, vcc
	global_store_dword v[18:19], v17, off offset:64
.LBB0_682:
	s_or_b64 exec, exec, s[0:1]
	v_mul_f32_e32 v17, v41, v16
	s_waitcnt lgkmcnt(0)
	s_nop 1
	v_mov_b32_dpp v18, v17 quad_perm:[1,0,3,2] row_mask:0xf bank_mask:0xf
	s_and_saveexec_b64 s[0:1], s[2:3]
	s_cbranch_execz .LBB0_684
	s_waitcnt lgkmcnt(0)
	v_cvt_pk_bf16_f32 v17, v17, v18
	v_add_co_u32_e32 v18, vcc, 0x22000, v0
	s_nop 1
	v_addc_co_u32_e32 v19, vcc, 0, v1, vcc
	global_store_dword v[18:19], v17, off offset:128
.LBB0_684:
	s_or_b64 exec, exec, s[0:1]
	v_mul_f32_e32 v16, v25, v16
	s_nop 1
	v_mov_b32_dpp v17, v16 quad_perm:[1,0,3,2] row_mask:0xf bank_mask:0xf
	s_and_saveexec_b64 s[0:1], s[2:3]
	s_cbranch_execz .LBB0_686
	s_waitcnt lgkmcnt(0)
	v_cvt_pk_bf16_f32 v18, v16, v17
	v_add_co_u32_e32 v16, vcc, 0x22000, v0
	s_nop 1
	v_addc_co_u32_e32 v17, vcc, 0, v1, vcc
	global_store_dword v[16:17], v18, off offset:192
.LBB0_686:
	s_or_b64 exec, exec, s[0:1]
	v_rcp_f32_e32 v16, v98
	s_waitcnt lgkmcnt(0)
	v_mul_f32_e32 v17, v74, v16
	s_nop 1
	v_mov_b32_dpp v18, v17 quad_perm:[1,0,3,2] row_mask:0xf bank_mask:0xf
	s_and_saveexec_b64 s[0:1], s[2:3]
	s_cbranch_execz .LBB0_688
	s_waitcnt lgkmcnt(0)
	v_cvt_pk_bf16_f32 v17, v17, v18
	v_add_co_u32_e32 v18, vcc, 0x24000, v0
	s_nop 1
	v_addc_co_u32_e32 v19, vcc, 0, v1, vcc
	global_store_dword v[18:19], v17, off
.LBB0_688:
	s_or_b64 exec, exec, s[0:1]
	v_mul_f32_e32 v17, v58, v16
	s_waitcnt lgkmcnt(0)
	s_nop 1
	v_mov_b32_dpp v18, v17 quad_perm:[1,0,3,2] row_mask:0xf bank_mask:0xf
	s_and_saveexec_b64 s[0:1], s[2:3]
	s_cbranch_execz .LBB0_690
	s_waitcnt lgkmcnt(0)
	v_cvt_pk_bf16_f32 v17, v17, v18
	v_add_co_u32_e32 v18, vcc, 0x24000, v0
	s_nop 1
	v_addc_co_u32_e32 v19, vcc, 0, v1, vcc
	global_store_dword v[18:19], v17, off offset:64
.LBB0_690:
	s_or_b64 exec, exec, s[0:1]
	v_mul_f32_e32 v17, v42, v16
	s_waitcnt lgkmcnt(0)
	s_nop 1
	v_mov_b32_dpp v18, v17 quad_perm:[1,0,3,2] row_mask:0xf bank_mask:0xf
	s_and_saveexec_b64 s[0:1], s[2:3]
	s_cbranch_execz .LBB0_692
	s_waitcnt lgkmcnt(0)
	v_cvt_pk_bf16_f32 v17, v17, v18
	v_add_co_u32_e32 v18, vcc, 0x24000, v0
	s_nop 1
	v_addc_co_u32_e32 v19, vcc, 0, v1, vcc
	global_store_dword v[18:19], v17, off offset:128
.LBB0_692:
	s_or_b64 exec, exec, s[0:1]
	v_mul_f32_e32 v16, v26, v16
	s_nop 1
	v_mov_b32_dpp v17, v16 quad_perm:[1,0,3,2] row_mask:0xf bank_mask:0xf
	s_and_saveexec_b64 s[0:1], s[2:3]
	s_cbranch_execz .LBB0_694
	s_waitcnt lgkmcnt(0)
	v_cvt_pk_bf16_f32 v18, v16, v17
	v_add_co_u32_e32 v16, vcc, 0x24000, v0
	s_nop 1
	v_addc_co_u32_e32 v17, vcc, 0, v1, vcc
	global_store_dword v[16:17], v18, off offset:192
.LBB0_694:
	s_or_b64 exec, exec, s[0:1]
	v_rcp_f32_e32 v16, v99
	s_waitcnt lgkmcnt(0)
	v_mul_f32_e32 v17, v75, v16
	s_nop 1
	v_mov_b32_dpp v18, v17 quad_perm:[1,0,3,2] row_mask:0xf bank_mask:0xf
	s_and_saveexec_b64 s[0:1], s[2:3]
	s_cbranch_execz .LBB0_696
	s_waitcnt lgkmcnt(0)
	v_cvt_pk_bf16_f32 v17, v17, v18
	v_add_co_u32_e32 v18, vcc, 0x26000, v0
	s_nop 1
	v_addc_co_u32_e32 v19, vcc, 0, v1, vcc
	global_store_dword v[18:19], v17, off
.LBB0_696:
	s_or_b64 exec, exec, s[0:1]
	v_mul_f32_e32 v17, v59, v16
	s_waitcnt lgkmcnt(0)
	s_nop 1
	v_mov_b32_dpp v18, v17 quad_perm:[1,0,3,2] row_mask:0xf bank_mask:0xf
	s_and_saveexec_b64 s[0:1], s[2:3]
	s_cbranch_execz .LBB0_698
	s_waitcnt lgkmcnt(0)
	v_cvt_pk_bf16_f32 v17, v17, v18
	v_add_co_u32_e32 v18, vcc, 0x26000, v0
	s_nop 1
	v_addc_co_u32_e32 v19, vcc, 0, v1, vcc
	global_store_dword v[18:19], v17, off offset:64
.LBB0_698:
	s_or_b64 exec, exec, s[0:1]
	v_mul_f32_e32 v17, v43, v16
	s_waitcnt lgkmcnt(0)
	s_nop 1
	v_mov_b32_dpp v18, v17 quad_perm:[1,0,3,2] row_mask:0xf bank_mask:0xf
	s_and_saveexec_b64 s[0:1], s[2:3]
	s_cbranch_execz .LBB0_700
	s_waitcnt lgkmcnt(0)
	v_cvt_pk_bf16_f32 v17, v17, v18
	v_add_co_u32_e32 v18, vcc, 0x26000, v0
	s_nop 1
	v_addc_co_u32_e32 v19, vcc, 0, v1, vcc
	global_store_dword v[18:19], v17, off offset:128
.LBB0_700:
	s_or_b64 exec, exec, s[0:1]
	v_mul_f32_e32 v16, v27, v16
	s_nop 1
	v_mov_b32_dpp v17, v16 quad_perm:[1,0,3,2] row_mask:0xf bank_mask:0xf
	s_and_saveexec_b64 s[0:1], s[2:3]
	s_cbranch_execz .LBB0_702
	s_waitcnt lgkmcnt(0)
	v_cvt_pk_bf16_f32 v18, v16, v17
	v_add_co_u32_e32 v16, vcc, 0x26000, v0
	s_nop 1
	v_addc_co_u32_e32 v17, vcc, 0, v1, vcc
	global_store_dword v[16:17], v18, off offset:192
.LBB0_702:
	s_or_b64 exec, exec, s[0:1]
	v_rcp_f32_e32 v16, v92
	s_waitcnt lgkmcnt(0)
	v_mul_f32_e32 v17, v76, v16
	s_nop 1
	v_mov_b32_dpp v18, v17 quad_perm:[1,0,3,2] row_mask:0xf bank_mask:0xf
	s_and_saveexec_b64 s[0:1], s[2:3]
	s_cbranch_execz .LBB0_704
	s_waitcnt lgkmcnt(0)
	v_cvt_pk_bf16_f32 v17, v17, v18
	v_add_co_u32_e32 v18, vcc, 0x30000, v0
	s_nop 1
	v_addc_co_u32_e32 v19, vcc, 0, v1, vcc
	global_store_dword v[18:19], v17, off
.LBB0_704:
	s_or_b64 exec, exec, s[0:1]
	v_mul_f32_e32 v17, v60, v16
	s_waitcnt lgkmcnt(0)
	s_nop 1
	v_mov_b32_dpp v18, v17 quad_perm:[1,0,3,2] row_mask:0xf bank_mask:0xf
	s_and_saveexec_b64 s[0:1], s[2:3]
	s_cbranch_execz .LBB0_706
	s_waitcnt lgkmcnt(0)
	v_cvt_pk_bf16_f32 v17, v17, v18
	v_add_co_u32_e32 v18, vcc, 0x30000, v0
	s_nop 1
	v_addc_co_u32_e32 v19, vcc, 0, v1, vcc
	global_store_dword v[18:19], v17, off offset:64
.LBB0_706:
	s_or_b64 exec, exec, s[0:1]
	v_mul_f32_e32 v17, v44, v16
	s_waitcnt lgkmcnt(0)
	s_nop 1
	v_mov_b32_dpp v18, v17 quad_perm:[1,0,3,2] row_mask:0xf bank_mask:0xf
	s_and_saveexec_b64 s[0:1], s[2:3]
	s_cbranch_execz .LBB0_708
	s_waitcnt lgkmcnt(0)
	v_cvt_pk_bf16_f32 v17, v17, v18
	v_add_co_u32_e32 v18, vcc, 0x30000, v0
	s_nop 1
	v_addc_co_u32_e32 v19, vcc, 0, v1, vcc
	global_store_dword v[18:19], v17, off offset:128
.LBB0_708:
	s_or_b64 exec, exec, s[0:1]
	v_mul_f32_e32 v16, v28, v16
	s_nop 1
	v_mov_b32_dpp v17, v16 quad_perm:[1,0,3,2] row_mask:0xf bank_mask:0xf
	s_and_saveexec_b64 s[0:1], s[2:3]
	s_cbranch_execz .LBB0_710
	s_waitcnt lgkmcnt(0)
	v_cvt_pk_bf16_f32 v18, v16, v17
	v_add_co_u32_e32 v16, vcc, 0x30000, v0
	s_nop 1
	v_addc_co_u32_e32 v17, vcc, 0, v1, vcc
	global_store_dword v[16:17], v18, off offset:192
.LBB0_710:
	s_or_b64 exec, exec, s[0:1]
	v_rcp_f32_e32 v16, v93
	s_waitcnt lgkmcnt(0)
	v_mul_f32_e32 v17, v77, v16
	s_nop 1
	v_mov_b32_dpp v18, v17 quad_perm:[1,0,3,2] row_mask:0xf bank_mask:0xf
	s_and_saveexec_b64 s[0:1], s[2:3]
	s_cbranch_execz .LBB0_712
	s_waitcnt lgkmcnt(0)
	v_cvt_pk_bf16_f32 v17, v17, v18
	v_add_co_u32_e32 v18, vcc, 0x32000, v0
	s_nop 1
	v_addc_co_u32_e32 v19, vcc, 0, v1, vcc
	global_store_dword v[18:19], v17, off
.LBB0_712:
	s_or_b64 exec, exec, s[0:1]
	v_mul_f32_e32 v17, v61, v16
	s_waitcnt lgkmcnt(0)
	s_nop 1
	v_mov_b32_dpp v18, v17 quad_perm:[1,0,3,2] row_mask:0xf bank_mask:0xf
	s_and_saveexec_b64 s[0:1], s[2:3]
	s_cbranch_execz .LBB0_714
	s_waitcnt lgkmcnt(0)
	v_cvt_pk_bf16_f32 v17, v17, v18
	v_add_co_u32_e32 v18, vcc, 0x32000, v0
	s_nop 1
	v_addc_co_u32_e32 v19, vcc, 0, v1, vcc
	global_store_dword v[18:19], v17, off offset:64
.LBB0_714:
	s_or_b64 exec, exec, s[0:1]
	v_mul_f32_e32 v17, v45, v16
	s_waitcnt lgkmcnt(0)
	s_nop 1
	v_mov_b32_dpp v18, v17 quad_perm:[1,0,3,2] row_mask:0xf bank_mask:0xf
	s_and_saveexec_b64 s[0:1], s[2:3]
	s_cbranch_execz .LBB0_716
	s_waitcnt lgkmcnt(0)
	v_cvt_pk_bf16_f32 v17, v17, v18
	v_add_co_u32_e32 v18, vcc, 0x32000, v0
	s_nop 1
	v_addc_co_u32_e32 v19, vcc, 0, v1, vcc
	global_store_dword v[18:19], v17, off offset:128
.LBB0_716:
	s_or_b64 exec, exec, s[0:1]
	v_mul_f32_e32 v16, v29, v16
	s_nop 1
	v_mov_b32_dpp v17, v16 quad_perm:[1,0,3,2] row_mask:0xf bank_mask:0xf
	s_and_saveexec_b64 s[0:1], s[2:3]
	s_cbranch_execz .LBB0_718
	s_waitcnt lgkmcnt(0)
	v_cvt_pk_bf16_f32 v18, v16, v17
	v_add_co_u32_e32 v16, vcc, 0x32000, v0
	s_nop 1
	v_addc_co_u32_e32 v17, vcc, 0, v1, vcc
	global_store_dword v[16:17], v18, off offset:192
.LBB0_718:
	s_or_b64 exec, exec, s[0:1]
	v_rcp_f32_e32 v16, v94
	s_waitcnt lgkmcnt(0)
	v_mul_f32_e32 v17, v78, v16
	s_nop 1
	v_mov_b32_dpp v18, v17 quad_perm:[1,0,3,2] row_mask:0xf bank_mask:0xf
	s_and_saveexec_b64 s[0:1], s[2:3]
	s_cbranch_execz .LBB0_720
	s_waitcnt lgkmcnt(0)
	v_cvt_pk_bf16_f32 v17, v17, v18
	v_add_co_u32_e32 v18, vcc, 0x34000, v0
	s_nop 1
	v_addc_co_u32_e32 v19, vcc, 0, v1, vcc
	global_store_dword v[18:19], v17, off
.LBB0_720:
	s_or_b64 exec, exec, s[0:1]
	v_mul_f32_e32 v17, v62, v16
	s_waitcnt lgkmcnt(0)
	s_nop 1
	v_mov_b32_dpp v18, v17 quad_perm:[1,0,3,2] row_mask:0xf bank_mask:0xf
	s_and_saveexec_b64 s[0:1], s[2:3]
	s_cbranch_execz .LBB0_722
	s_waitcnt lgkmcnt(0)
	v_cvt_pk_bf16_f32 v17, v17, v18
	v_add_co_u32_e32 v18, vcc, 0x34000, v0
	s_nop 1
	v_addc_co_u32_e32 v19, vcc, 0, v1, vcc
	global_store_dword v[18:19], v17, off offset:64
.LBB0_722:
	s_or_b64 exec, exec, s[0:1]
	v_mul_f32_e32 v17, v46, v16
	s_waitcnt lgkmcnt(0)
	s_nop 1
	v_mov_b32_dpp v18, v17 quad_perm:[1,0,3,2] row_mask:0xf bank_mask:0xf
	s_and_saveexec_b64 s[0:1], s[2:3]
	s_cbranch_execz .LBB0_724
	s_waitcnt lgkmcnt(0)
	v_cvt_pk_bf16_f32 v17, v17, v18
	v_add_co_u32_e32 v18, vcc, 0x34000, v0
	s_nop 1
	v_addc_co_u32_e32 v19, vcc, 0, v1, vcc
	global_store_dword v[18:19], v17, off offset:128
.LBB0_724:
	s_or_b64 exec, exec, s[0:1]
	v_mul_f32_e32 v16, v30, v16
	s_nop 1
	v_mov_b32_dpp v17, v16 quad_perm:[1,0,3,2] row_mask:0xf bank_mask:0xf
	s_and_saveexec_b64 s[0:1], s[2:3]
	s_cbranch_execz .LBB0_726
	s_waitcnt lgkmcnt(0)
	v_cvt_pk_bf16_f32 v18, v16, v17
	v_add_co_u32_e32 v16, vcc, 0x34000, v0
	s_nop 1
	v_addc_co_u32_e32 v17, vcc, 0, v1, vcc
	global_store_dword v[16:17], v18, off offset:192
.LBB0_726:
	s_or_b64 exec, exec, s[0:1]
	v_rcp_f32_e32 v16, v95
	s_waitcnt lgkmcnt(0)
	v_mul_f32_e32 v17, v79, v16
	s_nop 1
	v_mov_b32_dpp v18, v17 quad_perm:[1,0,3,2] row_mask:0xf bank_mask:0xf
	s_and_saveexec_b64 s[0:1], s[2:3]
	s_cbranch_execz .LBB0_728
	s_waitcnt lgkmcnt(0)
	v_cvt_pk_bf16_f32 v17, v17, v18
	v_add_co_u32_e32 v18, vcc, 0x36000, v0
	s_nop 1
	v_addc_co_u32_e32 v19, vcc, 0, v1, vcc
	global_store_dword v[18:19], v17, off
.LBB0_728:
	s_or_b64 exec, exec, s[0:1]
	v_mul_f32_e32 v17, v63, v16
	s_waitcnt lgkmcnt(0)
	s_nop 1
	v_mov_b32_dpp v18, v17 quad_perm:[1,0,3,2] row_mask:0xf bank_mask:0xf
	s_and_saveexec_b64 s[0:1], s[2:3]
	s_cbranch_execz .LBB0_730
	s_waitcnt lgkmcnt(0)
	v_cvt_pk_bf16_f32 v17, v17, v18
	v_add_co_u32_e32 v18, vcc, 0x36000, v0
	s_nop 1
	v_addc_co_u32_e32 v19, vcc, 0, v1, vcc
	global_store_dword v[18:19], v17, off offset:64
.LBB0_730:
	s_or_b64 exec, exec, s[0:1]
	v_mul_f32_e32 v17, v47, v16
	s_waitcnt lgkmcnt(0)
	s_nop 1
	v_mov_b32_dpp v18, v17 quad_perm:[1,0,3,2] row_mask:0xf bank_mask:0xf
	s_and_saveexec_b64 s[0:1], s[2:3]
	s_cbranch_execz .LBB0_732
	s_waitcnt lgkmcnt(0)
	v_cvt_pk_bf16_f32 v17, v17, v18
	v_add_co_u32_e32 v18, vcc, 0x36000, v0
	s_nop 1
	v_addc_co_u32_e32 v19, vcc, 0, v1, vcc
	global_store_dword v[18:19], v17, off offset:128
.LBB0_732:
	s_or_b64 exec, exec, s[0:1]
	v_mul_f32_e32 v16, v31, v16
	s_nop 1
	v_mov_b32_dpp v17, v16 quad_perm:[1,0,3,2] row_mask:0xf bank_mask:0xf
	s_and_saveexec_b64 s[0:1], s[2:3]
	s_cbranch_execz .LBB0_734
	v_add_co_u32_e32 v0, vcc, 0x36000, v0
	s_waitcnt lgkmcnt(0)
	v_cvt_pk_bf16_f32 v16, v16, v17
	s_nop 0
	v_addc_co_u32_e32 v1, vcc, 0, v1, vcc
	global_store_dword v[0:1], v16, off offset:192

.LBB0_1202:
	ds_read_b128 v[128:131], v176
	ds_read_b128 v[132:135], v176 offset:1024
	ds_read_b128 v[136:139], v176 offset:2048
	ds_read_b128 v[140:143], v176 offset:3072
	ds_read_b128 v[144:147], v177
	ds_read_b128 v[148:151], v177 offset:1024
	ds_read_b128 v[180:183], v177 offset:2048
	ds_read_b128 v[184:187], v177 offset:3072
	s_add_u32 s30, s28, 0xfff00080
	s_addc_u32 s31, s29, -1
	s_cmp_eq_u32 s40, 60
	s_cselect_b32 s35, s23, s31
	s_cselect_b32 s34, s36, s30
	s_cselect_b32 s31, s21, s39
	s_cselect_b32 s30, s37, s38
	v_lshl_add_u64 v[172:173], s[28:29], 0, v[164:165]
	s_add_i32 m0, s7, 0xc000
	s_nop 0
	global_load_lds_dwordx4 v[172:173], off
	v_lshl_add_u64 v[172:173], s[28:29], 0, v[166:167]
	s_add_i32 m0, s7, 0xe000
	s_nop 0
	global_load_lds_dwordx4 v[172:173], off
	ds_read_b128 v[188:191], v178
	ds_read_b128 v[192:195], v178 offset:1024
	ds_read_b128 v[196:199], v178 offset:2048
	ds_read_b128 v[200:203], v178 offset:3072
	ds_read_b128 v[204:207], v178 offset:4096
	ds_read_b128 v[208:211], v178 offset:5120
	ds_read_b128 v[212:215], v178 offset:6144
	ds_read_b128 v[216:219], v178 offset:7168
	s_waitcnt vmcnt(8)
	s_waitcnt lgkmcnt(0)
	s_barrier
	s_waitcnt lgkmcnt(0)
	v_mfma_f32_16x16x32_bf16 v[124:127], v[128:131], v[188:191], v[124:127]
	v_mfma_f32_16x16x32_bf16 v[124:127], v[132:135], v[192:195], v[124:127]
	v_mfma_f32_16x16x32_bf16 v[120:123], v[140:143], v[192:195], v[120:123]
	v_mfma_f32_16x16x32_bf16 v[120:123], v[136:139], v[188:191], v[120:123]
	v_mfma_f32_16x16x32_bf16 v[116:119], v[144:147], v[188:191], v[116:119]
	v_mfma_f32_16x16x32_bf16 v[116:119], v[148:151], v[192:195], v[116:119]
	v_mfma_f32_16x16x32_bf16 v[112:115], v[184:187], v[192:195], v[112:115]
	v_mfma_f32_16x16x32_bf16 v[112:115], v[180:183], v[188:191], v[112:115]
	v_mfma_f32_16x16x32_bf16 v[96:99], v[180:183], v[196:199], v[96:99]
	v_mfma_f32_16x16x32_bf16 v[96:99], v[184:187], v[200:203], v[96:99]
	v_mfma_f32_16x16x32_bf16 v[100:103], v[148:151], v[200:203], v[100:103]
	v_mfma_f32_16x16x32_bf16 v[100:103], v[144:147], v[196:199], v[100:103]
	v_mfma_f32_16x16x32_bf16 v[104:107], v[136:139], v[196:199], v[104:107]
	v_mfma_f32_16x16x32_bf16 v[104:107], v[140:143], v[200:203], v[104:107]
	v_mfma_f32_16x16x32_bf16 v[108:111], v[132:135], v[200:203], v[108:111]
	v_mfma_f32_16x16x32_bf16 v[108:111], v[128:131], v[196:199], v[108:111]
	v_mfma_f32_16x16x32_bf16 v[92:95], v[128:131], v[204:207], v[92:95]
	v_mfma_f32_16x16x32_bf16 v[92:95], v[132:135], v[208:211], v[92:95]
	v_mfma_f32_16x16x32_bf16 v[88:91], v[140:143], v[208:211], v[88:91]
	v_mfma_f32_16x16x32_bf16 v[88:91], v[136:139], v[204:207], v[88:91]
	v_mfma_f32_16x16x32_bf16 v[84:87], v[144:147], v[204:207], v[84:87]
	v_mfma_f32_16x16x32_bf16 v[84:87], v[148:151], v[208:211], v[84:87]
	v_mfma_f32_16x16x32_bf16 v[80:83], v[184:187], v[208:211], v[80:83]
	v_mfma_f32_16x16x32_bf16 v[80:83], v[180:183], v[204:207], v[80:83]
	v_mfma_f32_16x16x32_bf16 v[64:67], v[180:183], v[212:215], v[64:67]
	v_mfma_f32_16x16x32_bf16 v[64:67], v[184:187], v[216:219], v[64:67]
	v_mfma_f32_16x16x32_bf16 v[68:71], v[148:151], v[216:219], v[68:71]
	v_mfma_f32_16x16x32_bf16 v[68:71], v[144:147], v[212:215], v[68:71]
	v_mfma_f32_16x16x32_bf16 v[72:75], v[136:139], v[212:215], v[72:75]
	v_mfma_f32_16x16x32_bf16 v[72:75], v[140:143], v[216:219], v[72:75]
	v_mfma_f32_16x16x32_bf16 v[76:79], v[132:135], v[216:219], v[76:79]
	v_mfma_f32_16x16x32_bf16 v[76:79], v[128:131], v[212:215], v[76:79]
	s_barrier
	s_add_i32 s41, s68, s33
	v_lshl_add_u64 v[172:173], s[30:31], 0, v[154:155]
	s_mov_b32 m0, s41
	v_lshl_add_u64 v[220:221], s[30:31], 0, v[158:159]
	global_load_lds_dwordx4 v[172:173], off
	s_add_i32 m0, s41, 0x2000
	s_add_u32 s42, s30, 0x100000
	s_addc_u32 s43, s31, 0
	s_add_i32 s41, s69, s33
	global_load_lds_dwordx4 v[220:221], off
	v_lshl_add_u64 v[188:189], s[42:43], 0, v[154:155]
	s_mov_b32 m0, s41
	v_lshl_add_u64 v[222:223], s[34:35], 0, v[152:153]
	global_load_lds_dwordx4 v[188:189], off
	v_lshl_add_u64 v[188:189], s[42:43], 0, v[158:159]
	s_add_i32 m0, s41, 0x2000
	v_lshl_add_u64 v[224:225], s[34:35], 0, v[156:157]
	global_load_lds_dwordx4 v[188:189], off
	s_mov_b32 m0, s7
	s_nop 0
	global_load_lds_dwordx4 v[222:223], off
	s_mov_b32 m0, s59
	s_nop 0
	global_load_lds_dwordx4 v[224:225], off
	ds_read_b128 v[188:191], v178 offset:16384
	ds_read_b128 v[192:195], v178 offset:17408
	ds_read_b128 v[196:199], v178 offset:18432
	ds_read_b128 v[200:203], v178 offset:19456
	ds_read_b128 v[204:207], v178 offset:20480
	ds_read_b128 v[208:211], v178 offset:21504
	ds_read_b128 v[212:215], v178 offset:22528
	ds_read_b128 v[216:219], v178 offset:23552
	s_waitcnt vmcnt(8)
	s_waitcnt lgkmcnt(0)
	s_barrier
	s_waitcnt lgkmcnt(0)
	v_mfma_f32_16x16x32_bf16 v[60:63], v[128:131], v[188:191], v[60:63]
	v_mfma_f32_16x16x32_bf16 v[60:63], v[132:135], v[192:195], v[60:63]
	v_mfma_f32_16x16x32_bf16 v[56:59], v[140:143], v[192:195], v[56:59]
	v_mfma_f32_16x16x32_bf16 v[56:59], v[136:139], v[188:191], v[56:59]
	v_mfma_f32_16x16x32_bf16 v[52:55], v[144:147], v[188:191], v[52:55]
	v_mfma_f32_16x16x32_bf16 v[52:55], v[148:151], v[192:195], v[52:55]
	v_mfma_f32_16x16x32_bf16 v[48:51], v[184:187], v[192:195], v[48:51]
	v_mfma_f32_16x16x32_bf16 v[48:51], v[180:183], v[188:191], v[48:51]
	v_mfma_f32_16x16x32_bf16 v[32:35], v[180:183], v[196:199], v[32:35]
	v_mfma_f32_16x16x32_bf16 v[32:35], v[184:187], v[200:203], v[32:35]
	v_mfma_f32_16x16x32_bf16 v[36:39], v[148:151], v[200:203], v[36:39]
	v_mfma_f32_16x16x32_bf16 v[36:39], v[144:147], v[196:199], v[36:39]
	v_mfma_f32_16x16x32_bf16 v[40:43], v[136:139], v[196:199], v[40:43]
	v_mfma_f32_16x16x32_bf16 v[40:43], v[140:143], v[200:203], v[40:43]
	v_mfma_f32_16x16x32_bf16 v[44:47], v[132:135], v[200:203], v[44:47]
	v_mfma_f32_16x16x32_bf16 v[44:47], v[128:131], v[196:199], v[44:47]
	v_mfma_f32_16x16x32_bf16 v[28:31], v[128:131], v[204:207], v[28:31]
	v_mfma_f32_16x16x32_bf16 v[28:31], v[132:135], v[208:211], v[28:31]
	v_mfma_f32_16x16x32_bf16 v[24:27], v[140:143], v[208:211], v[24:27]
	v_mfma_f32_16x16x32_bf16 v[24:27], v[136:139], v[204:207], v[24:27]
	v_mfma_f32_16x16x32_bf16 v[20:23], v[144:147], v[204:207], v[20:23]
	v_mfma_f32_16x16x32_bf16 v[20:23], v[148:151], v[208:211], v[20:23]
	v_mfma_f32_16x16x32_bf16 v[16:19], v[184:187], v[208:211], v[16:19]
	v_mfma_f32_16x16x32_bf16 v[16:19], v[180:183], v[204:207], v[16:19]
	v_mfma_f32_16x16x32_bf16 v[0:3], v[180:183], v[212:215], v[0:3]
	v_mfma_f32_16x16x32_bf16 v[0:3], v[184:187], v[216:219], v[0:3]
	v_mfma_f32_16x16x32_bf16 v[4:7], v[148:151], v[216:219], v[4:7]
	v_mfma_f32_16x16x32_bf16 v[4:7], v[144:147], v[212:215], v[4:7]
	v_mfma_f32_16x16x32_bf16 v[8:11], v[136:139], v[212:215], v[8:11]
	v_mfma_f32_16x16x32_bf16 v[8:11], v[140:143], v[216:219], v[8:11]
	v_mfma_f32_16x16x32_bf16 v[12:15], v[132:135], v[216:219], v[12:15]
	v_mfma_f32_16x16x32_bf16 v[12:15], v[128:131], v[212:215], v[12:15]
	s_barrier
	s_add_i32 s41, 0, 0x18000
	s_add_i32 s42, 0, 0x1c000
	v_add_u32_e32 v140, s41, v174
	v_add_u32_e32 v184, s42, v174
	ds_read_b128 v[128:131], v140
	ds_read_b128 v[132:135], v140 offset:1024
	ds_read_b128 v[136:139], v140 offset:2048
	ds_read_b128 v[140:143], v140 offset:3072
	ds_read_b128 v[144:147], v184
	ds_read_b128 v[148:151], v184 offset:1024
	ds_read_b128 v[180:183], v184 offset:2048
	ds_read_b128 v[184:187], v184 offset:3072
	s_add_u32 s34, s34, 0x100000
	s_addc_u32 s35, s35, 0
	s_mov_b32 m0, s60
	v_lshl_add_u64 v[188:189], s[34:35], 0, v[152:153]
	global_load_lds_dwordx4 v[188:189], off
	v_lshl_add_u64 v[188:189], s[34:35], 0, v[156:157]
	s_mov_b32 m0, s61
	s_nop 0
	global_load_lds_dwordx4 v[188:189], off
	ds_read_b128 v[188:191], v178 offset:32768
	ds_read_b128 v[192:195], v178 offset:33792
	ds_read_b128 v[196:199], v178 offset:34816
	ds_read_b128 v[200:203], v178 offset:35840
	ds_read_b128 v[204:207], v178 offset:36864
	ds_read_b128 v[208:211], v178 offset:37888
	ds_read_b128 v[212:215], v178 offset:38912
	ds_read_b128 v[216:219], v178 offset:39936
	s_waitcnt vmcnt(8)
	s_waitcnt lgkmcnt(0)
	s_barrier
	s_waitcnt lgkmcnt(0)
	v_mfma_f32_16x16x32_bf16 v[124:127], v[128:131], v[188:191], v[124:127]
	v_mfma_f32_16x16x32_bf16 v[124:127], v[132:135], v[192:195], v[124:127]
	v_mfma_f32_16x16x32_bf16 v[120:123], v[140:143], v[192:195], v[120:123]
	v_mfma_f32_16x16x32_bf16 v[120:123], v[136:139], v[188:191], v[120:123]
	v_mfma_f32_16x16x32_bf16 v[116:119], v[144:147], v[188:191], v[116:119]
	v_mfma_f32_16x16x32_bf16 v[116:119], v[148:151], v[192:195], v[116:119]
	v_mfma_f32_16x16x32_bf16 v[112:115], v[184:187], v[192:195], v[112:115]
	v_mfma_f32_16x16x32_bf16 v[112:115], v[180:183], v[188:191], v[112:115]
	v_mfma_f32_16x16x32_bf16 v[96:99], v[180:183], v[196:199], v[96:99]
	v_mfma_f32_16x16x32_bf16 v[96:99], v[184:187], v[200:203], v[96:99]
	v_mfma_f32_16x16x32_bf16 v[100:103], v[148:151], v[200:203], v[100:103]
	v_mfma_f32_16x16x32_bf16 v[100:103], v[144:147], v[196:199], v[100:103]
	v_mfma_f32_16x16x32_bf16 v[104:107], v[136:139], v[196:199], v[104:107]
	v_mfma_f32_16x16x32_bf16 v[104:107], v[140:143], v[200:203], v[104:107]
	v_mfma_f32_16x16x32_bf16 v[108:111], v[132:135], v[200:203], v[108:111]
	v_mfma_f32_16x16x32_bf16 v[108:111], v[128:131], v[196:199], v[108:111]
	v_mfma_f32_16x16x32_bf16 v[92:95], v[128:131], v[204:207], v[92:95]
	v_mfma_f32_16x16x32_bf16 v[92:95], v[132:135], v[208:211], v[92:95]
	v_mfma_f32_16x16x32_bf16 v[88:91], v[140:143], v[208:211], v[88:91]
	v_mfma_f32_16x16x32_bf16 v[88:91], v[136:139], v[204:207], v[88:91]
	v_mfma_f32_16x16x32_bf16 v[84:87], v[144:147], v[204:207], v[84:87]
	v_mfma_f32_16x16x32_bf16 v[84:87], v[148:151], v[208:211], v[84:87]
	v_mfma_f32_16x16x32_bf16 v[80:83], v[184:187], v[208:211], v[80:83]
	v_mfma_f32_16x16x32_bf16 v[80:83], v[180:183], v[204:207], v[80:83]
	v_mfma_f32_16x16x32_bf16 v[64:67], v[180:183], v[212:215], v[64:67]
	v_mfma_f32_16x16x32_bf16 v[64:67], v[184:187], v[216:219], v[64:67]
	v_mfma_f32_16x16x32_bf16 v[68:71], v[148:151], v[216:219], v[68:71]
	v_mfma_f32_16x16x32_bf16 v[68:71], v[144:147], v[212:215], v[68:71]
	v_mfma_f32_16x16x32_bf16 v[72:75], v[136:139], v[212:215], v[72:75]
	v_mfma_f32_16x16x32_bf16 v[72:75], v[140:143], v[216:219], v[72:75]
	v_mfma_f32_16x16x32_bf16 v[76:79], v[132:135], v[216:219], v[76:79]
	v_mfma_f32_16x16x32_bf16 v[76:79], v[128:131], v[212:215], v[76:79]
	s_barrier
	s_add_i32 s34, s41, s33
	v_lshl_add_u64 v[172:173], v[172:173], 0, s[16:17]
	s_mov_b32 m0, s34
	s_nop 0
	global_load_lds_dwordx4 v[172:173], off
	s_add_i32 m0, s34, 0x2000
	s_add_u32 s30, s30, 0x100800
	v_lshl_add_u64 v[172:173], v[220:221], 0, s[16:17]
	s_addc_u32 s31, s31, 0
	s_add_i32 s34, s42, s33
	global_load_lds_dwordx4 v[172:173], off
	v_lshl_add_u64 v[172:173], s[30:31], 0, v[154:155]
	s_mov_b32 m0, s34
	s_nop 0
	global_load_lds_dwordx4 v[172:173], off
	v_lshl_add_u64 v[172:173], s[30:31], 0, v[158:159]
	s_add_i32 m0, s34, 0x2000
	s_nop 0
	global_load_lds_dwordx4 v[172:173], off
	v_lshl_add_u64 v[172:173], v[222:223], 0, s[18:19]
	s_mov_b32 m0, s63
	s_nop 0
	global_load_lds_dwordx4 v[172:173], off
	v_lshl_add_u64 v[172:173], v[224:225], 0, s[18:19]
	s_mov_b32 m0, s64
	s_nop 0
	global_load_lds_dwordx4 v[172:173], off
	ds_read_b128 v[188:191], v178 offset:49152
	ds_read_b128 v[192:195], v178 offset:50176
	ds_read_b128 v[196:199], v178 offset:51200
	ds_read_b128 v[200:203], v178 offset:52224
	ds_read_b128 v[204:207], v178 offset:53248
	ds_read_b128 v[208:211], v178 offset:54272
	ds_read_b128 v[212:215], v178 offset:55296
	ds_read_b128 v[216:219], v178 offset:56320
	s_waitcnt vmcnt(8)
	s_waitcnt lgkmcnt(0)
	s_barrier
	s_waitcnt lgkmcnt(0)
	v_mfma_f32_16x16x32_bf16 v[60:63], v[128:131], v[188:191], v[60:63]
	v_mfma_f32_16x16x32_bf16 v[60:63], v[132:135], v[192:195], v[60:63]
	v_mfma_f32_16x16x32_bf16 v[56:59], v[140:143], v[192:195], v[56:59]
	v_mfma_f32_16x16x32_bf16 v[56:59], v[136:139], v[188:191], v[56:59]
	v_mfma_f32_16x16x32_bf16 v[52:55], v[144:147], v[188:191], v[52:55]
	v_mfma_f32_16x16x32_bf16 v[52:55], v[148:151], v[192:195], v[52:55]
	v_mfma_f32_16x16x32_bf16 v[48:51], v[184:187], v[192:195], v[48:51]
	v_mfma_f32_16x16x32_bf16 v[48:51], v[180:183], v[188:191], v[48:51]
	v_mfma_f32_16x16x32_bf16 v[32:35], v[180:183], v[196:199], v[32:35]
	v_mfma_f32_16x16x32_bf16 v[32:35], v[184:187], v[200:203], v[32:35]
	v_mfma_f32_16x16x32_bf16 v[36:39], v[148:151], v[200:203], v[36:39]
	v_mfma_f32_16x16x32_bf16 v[36:39], v[144:147], v[196:199], v[36:39]
	v_mfma_f32_16x16x32_bf16 v[40:43], v[136:139], v[196:199], v[40:43]
	v_mfma_f32_16x16x32_bf16 v[40:43], v[140:143], v[200:203], v[40:43]
	v_mfma_f32_16x16x32_bf16 v[44:47], v[132:135], v[200:203], v[44:47]
	v_mfma_f32_16x16x32_bf16 v[44:47], v[128:131], v[196:199], v[44:47]
	v_mfma_f32_16x16x32_bf16 v[28:31], v[128:131], v[204:207], v[28:31]
	v_mfma_f32_16x16x32_bf16 v[28:31], v[132:135], v[208:211], v[28:31]
	v_mfma_f32_16x16x32_bf16 v[24:27], v[140:143], v[208:211], v[24:27]
	v_mfma_f32_16x16x32_bf16 v[24:27], v[136:139], v[204:207], v[24:27]
	v_mfma_f32_16x16x32_bf16 v[20:23], v[144:147], v[204:207], v[20:23]
	v_mfma_f32_16x16x32_bf16 v[20:23], v[148:151], v[208:211], v[20:23]
	v_mfma_f32_16x16x32_bf16 v[16:19], v[184:187], v[208:211], v[16:19]
	v_mfma_f32_16x16x32_bf16 v[16:19], v[180:183], v[204:207], v[16:19]
	v_mfma_f32_16x16x32_bf16 v[0:3], v[180:183], v[212:215], v[0:3]
	v_mfma_f32_16x16x32_bf16 v[0:3], v[184:187], v[216:219], v[0:3]
	v_mfma_f32_16x16x32_bf16 v[4:7], v[148:151], v[216:219], v[4:7]
	v_mfma_f32_16x16x32_bf16 v[4:7], v[144:147], v[212:215], v[4:7]
	v_mfma_f32_16x16x32_bf16 v[8:11], v[136:139], v[212:215], v[8:11]
	v_mfma_f32_16x16x32_bf16 v[8:11], v[140:143], v[216:219], v[8:11]
	v_mfma_f32_16x16x32_bf16 v[12:15], v[132:135], v[216:219], v[12:15]
	v_mfma_f32_16x16x32_bf16 v[12:15], v[128:131], v[212:215], v[12:15]
	s_barrier
	s_add_i32 s40, s40, 2
	s_add_u32 s38, s38, 0x1000
	s_addc_u32 s39, s39, 0
	s_add_u32 s28, s28, 0x100
	s_addc_u32 s29, s29, 0
	s_cmp_gt_u32 s40, 61
	s_cbranch_scc0 .LBB0_1202

.LBB0_1209:
	s_or_b64 exec, exec, s[40:41]
	s_and_b64 vcc, exec, s[10:11]
	s_cbranch_vccz .Lepibar_P5a
	s_barrier
.Lepibar_P5a:
	v_lshlrev_b32_e32 v96, 16, v140
	s_waitcnt lgkmcnt(0)
	v_and_b32_e32 v97, 0xffff0000, v140
	v_lshlrev_b32_e32 v98, 16, v141
	v_and_b32_e32 v99, 0xffff0000, v141
	v_lshlrev_b32_e32 v100, 16, v142
	v_and_b32_e32 v101, 0xffff0000, v142
	v_lshlrev_b32_e32 v102, 16, v143
	v_and_b32_e32 v103, 0xffff0000, v143
	v_pk_add_f32 v[94:95], v[94:95], v[98:99]
	v_pk_add_f32 v[92:93], v[92:93], v[96:97]
	v_pk_add_f32 v[96:97], v[90:91], v[102:103]
	v_pk_add_f32 v[90:91], v[88:89], v[100:101]
	v_mul_f32_e32 v88, v93, v93
	v_mul_f32_e32 v89, v95, v95
	v_fmac_f32_e32 v88, v92, v92
	v_fmac_f32_e32 v89, v94, v94
	v_add_f32_e32 v88, v88, v89
	v_mul_f32_e32 v89, v91, v91
	v_mul_f32_e32 v98, v97, v97
	v_fmac_f32_e32 v89, v90, v90
	v_fmac_f32_e32 v98, v96, v96
	v_lshlrev_b32_e32 v104, 16, v136
	v_and_b32_e32 v105, 0xffff0000, v136
	v_lshlrev_b32_e32 v106, 16, v137
	v_and_b32_e32 v107, 0xffff0000, v137
	v_add_f32_e32 v89, v89, v98
	v_lshlrev_b32_e32 v110, 16, v139
	v_and_b32_e32 v111, 0xffff0000, v139
	v_add_f32_e32 v98, v88, v89
	v_cvt_pk_bf16_f32 v88, v92, v93
	v_cvt_pk_bf16_f32 v89, v94, v95
	v_lshl_add_u64 v[92:93], v[160:161], 0, s[38:39]
	v_pk_add_f32 v[86:87], v[86:87], v[106:107]
	v_pk_add_f32 v[84:85], v[84:85], v[104:105]
	v_lshlrev_b32_e32 v108, 16, v138
	v_and_b32_e32 v109, 0xffff0000, v138
	v_cvt_pk_bf16_f32 v90, v90, v91
	v_cvt_pk_bf16_f32 v91, v96, v97
	global_store_dwordx4 v[92:93], v[88:91], off
	v_pk_add_f32 v[80:81], v[80:81], v[108:109]
	s_add_u32 s36, s36, s23
	v_pk_add_f32 v[88:89], v[82:83], v[110:111]
	v_mul_f32_e32 v82, v85, v85
	v_mul_f32_e32 v83, v87, v87
	v_fmac_f32_e32 v82, v84, v84
	v_fmac_f32_e32 v83, v86, v86
	v_add_f32_e32 v82, v82, v83
	v_mul_f32_e32 v83, v81, v81
	v_mul_f32_e32 v90, v89, v89
	v_fmac_f32_e32 v83, v80, v80
	v_fmac_f32_e32 v90, v88, v88
	v_add_f32_e32 v83, v83, v90
	v_add_f32_e32 v82, v82, v83
	v_add_f32_e32 v90, v98, v82
	ds_bpermute_b32 v91, v112, v90
	v_cvt_pk_bf16_f32 v82, v84, v85
	v_cvt_pk_bf16_f32 v83, v86, v87
	v_cvt_pk_bf16_f32 v84, v80, v81
	s_addc_u32 s37, s37, s21
	s_waitcnt lgkmcnt(0)
	v_add_f32_e32 v80, v90, v91
	ds_bpermute_b32 v81, v113, v80
	s_lshl_b64 s[36:37], s[36:37], 10
	v_lshl_add_u64 v[86:87], v[160:161], 0, s[36:37]
	v_cvt_pk_bf16_f32 v85, v88, v89
	global_store_dwordx4 v[86:87], v[82:85], off
	s_and_saveexec_b64 s[36:37], s[2:3]
	s_cbranch_execz .LBB0_1211
	v_or_b32_e32 v82, 32, v172
	v_ashrrev_i32_e32 v83, 31, v82
	s_waitcnt lgkmcnt(0)
	v_add_f32_e32 v84, v80, v81
	s_lshl_b32 s38, s6, 2
	v_lshlrev_b64 v[80:81], 8, v[82:83]
	s_ashr_i32 s39, s38, 31
	v_lshl_add_u64 v[80:81], s[14:15], 0, v[80:81]
	v_lshl_add_u64 v[80:81], s[38:39], 2, v[80:81]
	s_lshl_b32 s8, s62, 2
	v_lshl_add_u64 v[80:81], v[80:81], 0, s[8:9]
	global_store_dword v[80:81], v84, off

.LBB0_1435:
	ds_read_b128 v[128:131], v180
	ds_read_b128 v[132:135], v180 offset:1024
	ds_read_b128 v[136:139], v180 offset:2048
	ds_read_b128 v[140:143], v180 offset:3072
	ds_read_b128 v[144:147], v181
	ds_read_b128 v[148:151], v181 offset:1024
	ds_read_b128 v[170:173], v181 offset:2048
	ds_read_b128 v[174:177], v181 offset:3072
	s_add_u32 s26, s24, 0xfffc0080
	s_addc_u32 s27, s25, -1
	s_cmp_eq_u32 s35, 12
	s_cselect_b32 s29, s1, s27
	s_cselect_b32 s28, s19, s26
	s_cselect_b32 s27, s17, s34
	s_cselect_b32 s26, s30, s31
	v_lshl_add_u64 v[184:185], s[24:25], 0, v[162:163]
	s_add_i32 m0, s40, 0xc000
	s_nop 0
	global_load_lds_dwordx4 v[184:185], off
	v_lshl_add_u64 v[184:185], s[24:25], 0, v[164:165]
	s_add_i32 m0, s40, 0xe000
	s_nop 0
	global_load_lds_dwordx4 v[184:185], off
	ds_read_b128 v[184:187], v182
	ds_read_b128 v[188:191], v182 offset:1024
	ds_read_b128 v[192:195], v182 offset:2048
	ds_read_b128 v[196:199], v182 offset:3072
	ds_read_b128 v[200:203], v182 offset:4096
	ds_read_b128 v[204:207], v182 offset:5120
	ds_read_b128 v[208:211], v182 offset:6144
	ds_read_b128 v[212:215], v182 offset:7168
	s_waitcnt vmcnt(8)
	s_waitcnt lgkmcnt(0)
	s_barrier
	s_waitcnt lgkmcnt(0)
	v_mfma_f32_16x16x32_bf16 v[124:127], v[128:131], v[184:187], v[124:127]
	v_mfma_f32_16x16x32_bf16 v[124:127], v[132:135], v[188:191], v[124:127]
	v_mfma_f32_16x16x32_bf16 v[120:123], v[140:143], v[188:191], v[120:123]
	v_mfma_f32_16x16x32_bf16 v[120:123], v[136:139], v[184:187], v[120:123]
	v_mfma_f32_16x16x32_bf16 v[116:119], v[144:147], v[184:187], v[116:119]
	v_mfma_f32_16x16x32_bf16 v[116:119], v[148:151], v[188:191], v[116:119]
	v_mfma_f32_16x16x32_bf16 v[112:115], v[174:177], v[188:191], v[112:115]
	v_mfma_f32_16x16x32_bf16 v[112:115], v[170:173], v[184:187], v[112:115]
	v_mfma_f32_16x16x32_bf16 v[96:99], v[170:173], v[192:195], v[96:99]
	v_mfma_f32_16x16x32_bf16 v[96:99], v[174:177], v[196:199], v[96:99]
	v_mfma_f32_16x16x32_bf16 v[100:103], v[148:151], v[196:199], v[100:103]
	v_mfma_f32_16x16x32_bf16 v[100:103], v[144:147], v[192:195], v[100:103]
	v_mfma_f32_16x16x32_bf16 v[104:107], v[136:139], v[192:195], v[104:107]
	v_mfma_f32_16x16x32_bf16 v[104:107], v[140:143], v[196:199], v[104:107]
	v_mfma_f32_16x16x32_bf16 v[108:111], v[132:135], v[196:199], v[108:111]
	v_mfma_f32_16x16x32_bf16 v[108:111], v[128:131], v[192:195], v[108:111]
	v_mfma_f32_16x16x32_bf16 v[92:95], v[128:131], v[200:203], v[92:95]
	v_mfma_f32_16x16x32_bf16 v[92:95], v[132:135], v[204:207], v[92:95]
	v_mfma_f32_16x16x32_bf16 v[88:91], v[140:143], v[204:207], v[88:91]
	v_mfma_f32_16x16x32_bf16 v[88:91], v[136:139], v[200:203], v[88:91]
	v_mfma_f32_16x16x32_bf16 v[84:87], v[144:147], v[200:203], v[84:87]
	v_mfma_f32_16x16x32_bf16 v[84:87], v[148:151], v[204:207], v[84:87]
	v_mfma_f32_16x16x32_bf16 v[80:83], v[174:177], v[204:207], v[80:83]
	v_mfma_f32_16x16x32_bf16 v[80:83], v[170:173], v[200:203], v[80:83]
	v_mfma_f32_16x16x32_bf16 v[64:67], v[170:173], v[208:211], v[64:67]
	v_mfma_f32_16x16x32_bf16 v[64:67], v[174:177], v[212:215], v[64:67]
	v_mfma_f32_16x16x32_bf16 v[68:71], v[148:151], v[212:215], v[68:71]
	v_mfma_f32_16x16x32_bf16 v[68:71], v[144:147], v[208:211], v[68:71]
	v_mfma_f32_16x16x32_bf16 v[72:75], v[136:139], v[208:211], v[72:75]
	v_mfma_f32_16x16x32_bf16 v[72:75], v[140:143], v[212:215], v[72:75]
	v_mfma_f32_16x16x32_bf16 v[76:79], v[132:135], v[212:215], v[76:79]
	v_mfma_f32_16x16x32_bf16 v[76:79], v[128:131], v[208:211], v[76:79]
	s_barrier
	s_add_i32 s54, s50, s39
	v_lshl_add_u64 v[216:217], s[26:27], 0, v[154:155]
	s_mov_b32 m0, s54
	v_lshl_add_u64 v[218:219], s[26:27], 0, v[158:159]
	global_load_lds_dwordx4 v[216:217], off
	s_add_i32 m0, s54, 0x2000
	s_add_u32 s54, s26, 0x100000
	s_addc_u32 s55, s27, 0
	s_add_i32 s56, s51, s39
	global_load_lds_dwordx4 v[218:219], off
	v_lshl_add_u64 v[184:185], s[54:55], 0, v[154:155]
	s_mov_b32 m0, s56
	v_lshl_add_u64 v[220:221], s[28:29], 0, v[152:153]
	global_load_lds_dwordx4 v[184:185], off
	v_lshl_add_u64 v[184:185], s[54:55], 0, v[158:159]
	s_add_i32 m0, s56, 0x2000
	v_lshl_add_u64 v[222:223], s[28:29], 0, v[156:157]
	global_load_lds_dwordx4 v[184:185], off
	s_mov_b32 m0, s40
	s_nop 0
	global_load_lds_dwordx4 v[220:221], off
	s_mov_b32 m0, s41
	s_nop 0
	global_load_lds_dwordx4 v[222:223], off
	ds_read_b128 v[184:187], v182 offset:16384
	ds_read_b128 v[188:191], v182 offset:17408
	ds_read_b128 v[192:195], v182 offset:18432
	ds_read_b128 v[196:199], v182 offset:19456
	ds_read_b128 v[200:203], v182 offset:20480
	ds_read_b128 v[204:207], v182 offset:21504
	ds_read_b128 v[208:211], v182 offset:22528
	ds_read_b128 v[212:215], v182 offset:23552
	s_waitcnt vmcnt(8)
	s_waitcnt lgkmcnt(0)
	s_barrier
	s_waitcnt lgkmcnt(0)
	v_mfma_f32_16x16x32_bf16 v[60:63], v[128:131], v[184:187], v[60:63]
	v_mfma_f32_16x16x32_bf16 v[60:63], v[132:135], v[188:191], v[60:63]
	v_mfma_f32_16x16x32_bf16 v[56:59], v[140:143], v[188:191], v[56:59]
	v_mfma_f32_16x16x32_bf16 v[56:59], v[136:139], v[184:187], v[56:59]
	v_mfma_f32_16x16x32_bf16 v[52:55], v[144:147], v[184:187], v[52:55]
	v_mfma_f32_16x16x32_bf16 v[52:55], v[148:151], v[188:191], v[52:55]
	v_mfma_f32_16x16x32_bf16 v[48:51], v[174:177], v[188:191], v[48:51]
	v_mfma_f32_16x16x32_bf16 v[48:51], v[170:173], v[184:187], v[48:51]
	v_mfma_f32_16x16x32_bf16 v[32:35], v[170:173], v[192:195], v[32:35]
	v_mfma_f32_16x16x32_bf16 v[32:35], v[174:177], v[196:199], v[32:35]
	v_mfma_f32_16x16x32_bf16 v[36:39], v[148:151], v[196:199], v[36:39]
	v_mfma_f32_16x16x32_bf16 v[36:39], v[144:147], v[192:195], v[36:39]
	v_mfma_f32_16x16x32_bf16 v[40:43], v[136:139], v[192:195], v[40:43]
	v_mfma_f32_16x16x32_bf16 v[40:43], v[140:143], v[196:199], v[40:43]
	v_mfma_f32_16x16x32_bf16 v[44:47], v[132:135], v[196:199], v[44:47]
	v_mfma_f32_16x16x32_bf16 v[44:47], v[128:131], v[192:195], v[44:47]
	v_mfma_f32_16x16x32_bf16 v[28:31], v[128:131], v[200:203], v[28:31]
	v_mfma_f32_16x16x32_bf16 v[28:31], v[132:135], v[204:207], v[28:31]
	v_mfma_f32_16x16x32_bf16 v[24:27], v[140:143], v[204:207], v[24:27]
	v_mfma_f32_16x16x32_bf16 v[24:27], v[136:139], v[200:203], v[24:27]
	v_mfma_f32_16x16x32_bf16 v[20:23], v[144:147], v[200:203], v[20:23]
	v_mfma_f32_16x16x32_bf16 v[20:23], v[148:151], v[204:207], v[20:23]
	v_mfma_f32_16x16x32_bf16 v[16:19], v[174:177], v[204:207], v[16:19]
	v_mfma_f32_16x16x32_bf16 v[16:19], v[170:173], v[200:203], v[16:19]
	v_mfma_f32_16x16x32_bf16 v[0:3], v[170:173], v[208:211], v[0:3]
	v_mfma_f32_16x16x32_bf16 v[0:3], v[174:177], v[212:215], v[0:3]
	v_mfma_f32_16x16x32_bf16 v[4:7], v[148:151], v[212:215], v[4:7]
	v_mfma_f32_16x16x32_bf16 v[4:7], v[144:147], v[208:211], v[4:7]
	v_mfma_f32_16x16x32_bf16 v[8:11], v[136:139], v[208:211], v[8:11]
	v_mfma_f32_16x16x32_bf16 v[8:11], v[140:143], v[212:215], v[8:11]
	v_mfma_f32_16x16x32_bf16 v[12:15], v[132:135], v[212:215], v[12:15]
	v_mfma_f32_16x16x32_bf16 v[12:15], v[128:131], v[208:211], v[12:15]
	s_barrier
	s_add_i32 s54, 0, 0x18000
	s_add_i32 s55, 0, 0x1c000
	v_add_u32_e32 v140, s54, v178
	v_add_u32_e32 v174, s55, v178
	ds_read_b128 v[128:131], v140
	ds_read_b128 v[132:135], v140 offset:1024
	ds_read_b128 v[136:139], v140 offset:2048
	ds_read_b128 v[140:143], v140 offset:3072
	ds_read_b128 v[144:147], v174
	ds_read_b128 v[148:151], v174 offset:1024
	ds_read_b128 v[170:173], v174 offset:2048
	ds_read_b128 v[174:177], v174 offset:3072
	s_add_u32 s28, s28, 0x40000
	s_addc_u32 s29, s29, 0
	s_mov_b32 m0, s42
	v_lshl_add_u64 v[184:185], s[28:29], 0, v[152:153]
	global_load_lds_dwordx4 v[184:185], off
	v_lshl_add_u64 v[184:185], s[28:29], 0, v[156:157]
	s_mov_b32 m0, s43
	s_nop 0
	global_load_lds_dwordx4 v[184:185], off
	ds_read_b128 v[184:187], v182 offset:32768
	ds_read_b128 v[188:191], v182 offset:33792
	ds_read_b128 v[192:195], v182 offset:34816
	ds_read_b128 v[196:199], v182 offset:35840
	ds_read_b128 v[200:203], v182 offset:36864
	ds_read_b128 v[204:207], v182 offset:37888
	ds_read_b128 v[208:211], v182 offset:38912
	ds_read_b128 v[212:215], v182 offset:39936
	s_waitcnt vmcnt(8)
	s_waitcnt lgkmcnt(0)
	s_barrier
	s_waitcnt lgkmcnt(0)
	v_mfma_f32_16x16x32_bf16 v[124:127], v[128:131], v[184:187], v[124:127]
	v_mfma_f32_16x16x32_bf16 v[124:127], v[132:135], v[188:191], v[124:127]
	v_mfma_f32_16x16x32_bf16 v[120:123], v[140:143], v[188:191], v[120:123]
	v_mfma_f32_16x16x32_bf16 v[120:123], v[136:139], v[184:187], v[120:123]
	v_mfma_f32_16x16x32_bf16 v[116:119], v[144:147], v[184:187], v[116:119]
	v_mfma_f32_16x16x32_bf16 v[116:119], v[148:151], v[188:191], v[116:119]
	v_mfma_f32_16x16x32_bf16 v[112:115], v[174:177], v[188:191], v[112:115]
	v_mfma_f32_16x16x32_bf16 v[112:115], v[170:173], v[184:187], v[112:115]
	v_mfma_f32_16x16x32_bf16 v[96:99], v[170:173], v[192:195], v[96:99]
	v_mfma_f32_16x16x32_bf16 v[96:99], v[174:177], v[196:199], v[96:99]
	v_mfma_f32_16x16x32_bf16 v[100:103], v[148:151], v[196:199], v[100:103]
	v_mfma_f32_16x16x32_bf16 v[100:103], v[144:147], v[192:195], v[100:103]
	v_mfma_f32_16x16x32_bf16 v[104:107], v[136:139], v[192:195], v[104:107]
	v_mfma_f32_16x16x32_bf16 v[104:107], v[140:143], v[196:199], v[104:107]
	v_mfma_f32_16x16x32_bf16 v[108:111], v[132:135], v[196:199], v[108:111]
	v_mfma_f32_16x16x32_bf16 v[108:111], v[128:131], v[192:195], v[108:111]
	v_mfma_f32_16x16x32_bf16 v[92:95], v[128:131], v[200:203], v[92:95]
	v_mfma_f32_16x16x32_bf16 v[92:95], v[132:135], v[204:207], v[92:95]
	v_mfma_f32_16x16x32_bf16 v[88:91], v[140:143], v[204:207], v[88:91]
	v_mfma_f32_16x16x32_bf16 v[88:91], v[136:139], v[200:203], v[88:91]
	v_mfma_f32_16x16x32_bf16 v[84:87], v[144:147], v[200:203], v[84:87]
	v_mfma_f32_16x16x32_bf16 v[84:87], v[148:151], v[204:207], v[84:87]
	v_mfma_f32_16x16x32_bf16 v[80:83], v[174:177], v[204:207], v[80:83]
	v_mfma_f32_16x16x32_bf16 v[80:83], v[170:173], v[200:203], v[80:83]
	v_mfma_f32_16x16x32_bf16 v[64:67], v[170:173], v[208:211], v[64:67]
	v_mfma_f32_16x16x32_bf16 v[64:67], v[174:177], v[212:215], v[64:67]
	v_mfma_f32_16x16x32_bf16 v[68:71], v[148:151], v[212:215], v[68:71]
	v_mfma_f32_16x16x32_bf16 v[68:71], v[144:147], v[208:211], v[68:71]
	v_mfma_f32_16x16x32_bf16 v[72:75], v[136:139], v[208:211], v[72:75]
	v_mfma_f32_16x16x32_bf16 v[72:75], v[140:143], v[212:215], v[72:75]
	v_mfma_f32_16x16x32_bf16 v[76:79], v[132:135], v[212:215], v[76:79]
	v_mfma_f32_16x16x32_bf16 v[76:79], v[128:131], v[208:211], v[76:79]
	s_barrier
	s_add_i32 s28, s54, s39
	v_lshl_add_u64 v[184:185], v[216:217], 0, s[14:15]
	s_mov_b32 m0, s28
	s_nop 0
	global_load_lds_dwordx4 v[184:185], off
	s_add_i32 m0, s28, 0x2000
	s_add_u32 s26, s26, 0x100080
	v_lshl_add_u64 v[184:185], v[218:219], 0, s[14:15]
	s_addc_u32 s27, s27, 0
	s_add_i32 s28, s55, s39
	global_load_lds_dwordx4 v[184:185], off
	v_lshl_add_u64 v[184:185], s[26:27], 0, v[154:155]
	s_mov_b32 m0, s28
	s_nop 0
	global_load_lds_dwordx4 v[184:185], off
	v_lshl_add_u64 v[184:185], s[26:27], 0, v[158:159]
	s_add_i32 m0, s28, 0x2000
	s_nop 0
	global_load_lds_dwordx4 v[184:185], off
	v_lshl_add_u64 v[184:185], v[220:221], 0, s[14:15]
	s_mov_b32 m0, s45
	s_nop 0
	global_load_lds_dwordx4 v[184:185], off
	v_lshl_add_u64 v[184:185], v[222:223], 0, s[14:15]
	s_mov_b32 m0, s46
	s_nop 0
	global_load_lds_dwordx4 v[184:185], off
	ds_read_b128 v[184:187], v182 offset:49152
	ds_read_b128 v[188:191], v182 offset:50176
	ds_read_b128 v[192:195], v182 offset:51200
	ds_read_b128 v[196:199], v182 offset:52224
	ds_read_b128 v[200:203], v182 offset:53248
	ds_read_b128 v[204:207], v182 offset:54272
	ds_read_b128 v[208:211], v182 offset:55296
	ds_read_b128 v[212:215], v182 offset:56320
	s_waitcnt vmcnt(8)
	s_waitcnt lgkmcnt(0)
	s_barrier
	s_waitcnt lgkmcnt(0)
	v_mfma_f32_16x16x32_bf16 v[60:63], v[128:131], v[184:187], v[60:63]
	v_mfma_f32_16x16x32_bf16 v[60:63], v[132:135], v[188:191], v[60:63]
	v_mfma_f32_16x16x32_bf16 v[56:59], v[140:143], v[188:191], v[56:59]
	v_mfma_f32_16x16x32_bf16 v[56:59], v[136:139], v[184:187], v[56:59]
	v_mfma_f32_16x16x32_bf16 v[52:55], v[144:147], v[184:187], v[52:55]
	v_mfma_f32_16x16x32_bf16 v[52:55], v[148:151], v[188:191], v[52:55]
	v_mfma_f32_16x16x32_bf16 v[48:51], v[174:177], v[188:191], v[48:51]
	v_mfma_f32_16x16x32_bf16 v[48:51], v[170:173], v[184:187], v[48:51]
	v_mfma_f32_16x16x32_bf16 v[32:35], v[170:173], v[192:195], v[32:35]
	v_mfma_f32_16x16x32_bf16 v[32:35], v[174:177], v[196:199], v[32:35]
	v_mfma_f32_16x16x32_bf16 v[36:39], v[148:151], v[196:199], v[36:39]
	v_mfma_f32_16x16x32_bf16 v[36:39], v[144:147], v[192:195], v[36:39]
	v_mfma_f32_16x16x32_bf16 v[40:43], v[136:139], v[192:195], v[40:43]
	v_mfma_f32_16x16x32_bf16 v[40:43], v[140:143], v[196:199], v[40:43]
	v_mfma_f32_16x16x32_bf16 v[44:47], v[132:135], v[196:199], v[44:47]
	v_mfma_f32_16x16x32_bf16 v[44:47], v[128:131], v[192:195], v[44:47]
	v_mfma_f32_16x16x32_bf16 v[28:31], v[128:131], v[200:203], v[28:31]
	v_mfma_f32_16x16x32_bf16 v[28:31], v[132:135], v[204:207], v[28:31]
	v_mfma_f32_16x16x32_bf16 v[24:27], v[140:143], v[204:207], v[24:27]
	v_mfma_f32_16x16x32_bf16 v[24:27], v[136:139], v[200:203], v[24:27]
	v_mfma_f32_16x16x32_bf16 v[20:23], v[144:147], v[200:203], v[20:23]
	v_mfma_f32_16x16x32_bf16 v[20:23], v[148:151], v[204:207], v[20:23]
	v_mfma_f32_16x16x32_bf16 v[16:19], v[174:177], v[204:207], v[16:19]
	v_mfma_f32_16x16x32_bf16 v[16:19], v[170:173], v[200:203], v[16:19]
	v_mfma_f32_16x16x32_bf16 v[0:3], v[170:173], v[208:211], v[0:3]
	v_mfma_f32_16x16x32_bf16 v[0:3], v[174:177], v[212:215], v[0:3]
	v_mfma_f32_16x16x32_bf16 v[4:7], v[148:151], v[212:215], v[4:7]
	v_mfma_f32_16x16x32_bf16 v[4:7], v[144:147], v[208:211], v[4:7]
	v_mfma_f32_16x16x32_bf16 v[8:11], v[136:139], v[208:211], v[8:11]
	v_mfma_f32_16x16x32_bf16 v[8:11], v[140:143], v[212:215], v[8:11]
	v_mfma_f32_16x16x32_bf16 v[12:15], v[132:135], v[212:215], v[12:15]
	v_mfma_f32_16x16x32_bf16 v[12:15], v[128:131], v[208:211], v[12:15]
	s_barrier
	s_add_i32 s35, s35, 2
	s_add_u32 s24, s24, 0x100
	s_addc_u32 s25, s25, 0
	s_add_u32 s31, s31, 0x100
	s_addc_u32 s34, s34, 0
	s_cmp_gt_u32 s35, 13
	s_cbranch_scc0 .LBB0_1435

.LBB0_1442:
	s_or_b64 exec, exec, s[30:31]
	s_and_b64 vcc, exec, s[8:9]
	s_cbranch_vccz .Lepibar_P7
	s_barrier
.Lepibar_P7:
	v_lshlrev_b32_e32 v96, 16, v136
	s_waitcnt lgkmcnt(0)
	v_and_b32_e32 v97, 0xffff0000, v136
	v_lshlrev_b32_e32 v98, 16, v137
	v_and_b32_e32 v99, 0xffff0000, v137
	v_lshlrev_b32_e32 v100, 16, v138
	v_and_b32_e32 v101, 0xffff0000, v138
	v_lshlrev_b32_e32 v102, 16, v139
	v_and_b32_e32 v103, 0xffff0000, v139
	v_pk_add_f32 v[94:95], v[94:95], v[98:99]
	v_pk_add_f32 v[92:93], v[92:93], v[96:97]
	v_pk_add_f32 v[96:97], v[90:91], v[102:103]
	v_pk_add_f32 v[90:91], v[88:89], v[100:101]
	v_mul_f32_e32 v88, v93, v93
	v_mul_f32_e32 v89, v95, v95
	v_fmac_f32_e32 v88, v92, v92
	v_fmac_f32_e32 v89, v94, v94
	v_add_f32_e32 v88, v88, v89
	v_mul_f32_e32 v89, v91, v91
	v_mul_f32_e32 v98, v97, v97
	v_fmac_f32_e32 v89, v90, v90
	v_fmac_f32_e32 v98, v96, v96
	v_lshlrev_b32_e32 v104, 16, v140
	v_and_b32_e32 v105, 0xffff0000, v140
	v_lshlrev_b32_e32 v106, 16, v141
	v_and_b32_e32 v107, 0xffff0000, v141
	v_add_f32_e32 v89, v89, v98
	v_lshlrev_b32_e32 v110, 16, v143
	v_and_b32_e32 v111, 0xffff0000, v143
	v_add_f32_e32 v98, v88, v89
	v_cvt_pk_bf16_f32 v88, v92, v93
	v_cvt_pk_bf16_f32 v89, v94, v95
	v_pk_add_f32 v[86:87], v[86:87], v[106:107]
	v_pk_add_f32 v[84:85], v[84:85], v[104:105]
	v_lshlrev_b32_e32 v108, 16, v142
	v_and_b32_e32 v109, 0xffff0000, v142
	v_cvt_pk_bf16_f32 v90, v90, v91
	v_cvt_pk_bf16_f32 v91, v96, v97
	global_store_dwordx4 v[174:175], v[88:91], off
	v_pk_add_f32 v[80:81], v[80:81], v[108:109]
	s_add_u32 s28, s28, s17
	v_pk_add_f32 v[88:89], v[82:83], v[110:111]
	v_mul_f32_e32 v82, v85, v85
	v_mul_f32_e32 v83, v87, v87
	v_fmac_f32_e32 v82, v84, v84
	v_fmac_f32_e32 v83, v86, v86
	v_add_f32_e32 v82, v82, v83
	v_mul_f32_e32 v83, v81, v81
	v_mul_f32_e32 v90, v89, v89
	v_fmac_f32_e32 v83, v80, v80
	v_fmac_f32_e32 v90, v88, v88
	v_add_f32_e32 v83, v83, v90
	v_add_f32_e32 v82, v82, v83
	v_add_f32_e32 v90, v98, v82
	ds_bpermute_b32 v91, v112, v90
	v_cvt_pk_bf16_f32 v82, v84, v85
	v_cvt_pk_bf16_f32 v83, v86, v87
	v_cvt_pk_bf16_f32 v84, v80, v81
	s_addc_u32 s29, s29, s1
	s_waitcnt lgkmcnt(0)
	v_add_f32_e32 v80, v90, v91
	ds_bpermute_b32 v81, v113, v80
	s_lshl_b64 s[28:29], s[28:29], 10
	v_lshl_add_u64 v[86:87], v[160:161], 0, s[28:29]
	v_cvt_pk_bf16_f32 v85, v88, v89
	global_store_dwordx4 v[86:87], v[82:85], off
	s_and_saveexec_b64 s[28:29], s[2:3]
	s_cbranch_execz .LBB0_1444
	v_or_b32_e32 v82, 32, v170
	v_ashrrev_i32_e32 v83, 31, v82
	s_waitcnt lgkmcnt(0)
	v_add_f32_e32 v84, v80, v81
	s_lshl_b32 s30, s0, 2
	v_lshlrev_b64 v[80:81], 8, v[82:83]
	s_ashr_i32 s31, s30, 31
	v_lshl_add_u64 v[80:81], s[12:13], 0, v[80:81]
	v_lshl_add_u64 v[80:81], s[30:31], 2, v[80:81]
	s_lshl_b32 s6, s44, 2
	v_lshl_add_u64 v[80:81], v[80:81], 0, s[6:7]
	global_store_dword v[80:81], v84, off

.LBB0_1543:
	ds_read_b128 v[128:131], v167
	ds_read_b128 v[154:157], v167 offset:1024
	ds_read_b128 v[172:175], v167 offset:2048
	ds_read_b128 v[176:179], v167 offset:3072
	ds_read_b128 v[180:183], v168
	ds_read_b128 v[184:187], v168 offset:1024
	ds_read_b128 v[188:191], v168 offset:2048
	ds_read_b128 v[192:195], v168 offset:3072
	s_add_u32 s22, s20, 0x1000
	s_addc_u32 s23, s21, 0
	s_cmp_eq_u32 s54, 60
	s_cselect_b32 s27, s13, s23
	s_cselect_b32 s26, s50, s22
	s_cselect_b32 s25, s11, s53
	s_cselect_b32 s24, s51, s52
	v_lshl_add_u64 v[160:161], s[20:21], 0, v[144:145]
	s_add_i32 m0, s19, 0xc000
	s_nop 0
	global_load_lds_dwordx4 v[160:161], off
	v_lshl_add_u64 v[160:161], s[20:21], 0, v[146:147]
	s_add_i32 m0, s19, 0xe000
	s_nop 0
	global_load_lds_dwordx4 v[160:161], off
	ds_read_b128 v[196:199], v169
	ds_read_b128 v[200:203], v169 offset:1024
	ds_read_b128 v[204:207], v169 offset:2048
	ds_read_b128 v[208:211], v169 offset:3072
	ds_read_b128 v[212:215], v169 offset:4096
	ds_read_b128 v[216:219], v169 offset:5120
	ds_read_b128 v[220:223], v169 offset:6144
	ds_read_b128 v[224:227], v169 offset:7168
	s_waitcnt vmcnt(8)
	s_waitcnt lgkmcnt(0)
	s_barrier
	s_waitcnt lgkmcnt(0)
	v_mfma_f32_16x16x32_bf16 v[124:127], v[128:131], v[196:199], v[124:127]
	v_mfma_f32_16x16x32_bf16 v[124:127], v[154:157], v[200:203], v[124:127]
	v_mfma_f32_16x16x32_bf16 v[120:123], v[176:179], v[200:203], v[120:123]
	v_mfma_f32_16x16x32_bf16 v[120:123], v[172:175], v[196:199], v[120:123]
	v_mfma_f32_16x16x32_bf16 v[116:119], v[180:183], v[196:199], v[116:119]
	v_mfma_f32_16x16x32_bf16 v[116:119], v[184:187], v[200:203], v[116:119]
	v_mfma_f32_16x16x32_bf16 v[112:115], v[192:195], v[200:203], v[112:115]
	v_mfma_f32_16x16x32_bf16 v[112:115], v[188:191], v[196:199], v[112:115]
	v_mfma_f32_16x16x32_bf16 v[96:99], v[188:191], v[204:207], v[96:99]
	v_mfma_f32_16x16x32_bf16 v[96:99], v[192:195], v[208:211], v[96:99]
	v_mfma_f32_16x16x32_bf16 v[100:103], v[184:187], v[208:211], v[100:103]
	v_mfma_f32_16x16x32_bf16 v[100:103], v[180:183], v[204:207], v[100:103]
	v_mfma_f32_16x16x32_bf16 v[104:107], v[172:175], v[204:207], v[104:107]
	v_mfma_f32_16x16x32_bf16 v[104:107], v[176:179], v[208:211], v[104:107]
	v_mfma_f32_16x16x32_bf16 v[108:111], v[154:157], v[208:211], v[108:111]
	v_mfma_f32_16x16x32_bf16 v[108:111], v[128:131], v[204:207], v[108:111]
	v_mfma_f32_16x16x32_bf16 v[92:95], v[128:131], v[212:215], v[92:95]
	v_mfma_f32_16x16x32_bf16 v[92:95], v[154:157], v[216:219], v[92:95]
	v_mfma_f32_16x16x32_bf16 v[88:91], v[176:179], v[216:219], v[88:91]
	v_mfma_f32_16x16x32_bf16 v[88:91], v[172:175], v[212:215], v[88:91]
	v_mfma_f32_16x16x32_bf16 v[84:87], v[180:183], v[212:215], v[84:87]
	v_mfma_f32_16x16x32_bf16 v[84:87], v[184:187], v[216:219], v[84:87]
	v_mfma_f32_16x16x32_bf16 v[80:83], v[192:195], v[216:219], v[80:83]
	v_mfma_f32_16x16x32_bf16 v[80:83], v[188:191], v[212:215], v[80:83]
	v_mfma_f32_16x16x32_bf16 v[64:67], v[188:191], v[220:223], v[64:67]
	v_mfma_f32_16x16x32_bf16 v[64:67], v[192:195], v[224:227], v[64:67]
	v_mfma_f32_16x16x32_bf16 v[68:71], v[184:187], v[224:227], v[68:71]
	v_mfma_f32_16x16x32_bf16 v[68:71], v[180:183], v[220:223], v[68:71]
	v_mfma_f32_16x16x32_bf16 v[72:75], v[172:175], v[220:223], v[72:75]
	v_mfma_f32_16x16x32_bf16 v[72:75], v[176:179], v[224:227], v[72:75]
	v_mfma_f32_16x16x32_bf16 v[76:79], v[154:157], v[224:227], v[76:79]
	v_mfma_f32_16x16x32_bf16 v[76:79], v[128:131], v[220:223], v[76:79]
	s_barrier
	s_add_i32 s20, s45, s30
	v_lshl_add_u64 v[160:161], s[24:25], 0, v[134:135]
	s_mov_b32 m0, s20
	v_lshl_add_u64 v[164:165], s[24:25], 0, v[138:139]
	global_load_lds_dwordx4 v[160:161], off
	s_add_i32 m0, s20, 0x2000
	s_add_u32 s20, s24, 0x100000
	s_addc_u32 s21, s25, 0
	s_add_i32 s55, s46, s30
	global_load_lds_dwordx4 v[164:165], off
	v_lshl_add_u64 v[196:197], s[20:21], 0, v[134:135]
	s_mov_b32 m0, s55
	v_lshl_add_u64 v[228:229], s[26:27], 0, v[132:133]
	global_load_lds_dwordx4 v[196:197], off
	v_lshl_add_u64 v[196:197], s[20:21], 0, v[138:139]
	s_add_i32 m0, s55, 0x2000
	v_lshl_add_u64 v[230:231], s[26:27], 0, v[136:137]
	global_load_lds_dwordx4 v[196:197], off
	s_mov_b32 m0, s19
	s_nop 0
	global_load_lds_dwordx4 v[228:229], off
	s_mov_b32 m0, s36
	s_nop 0
	global_load_lds_dwordx4 v[230:231], off
	ds_read_b128 v[196:199], v169 offset:16384
	ds_read_b128 v[200:203], v169 offset:17408
	ds_read_b128 v[204:207], v169 offset:18432
	ds_read_b128 v[208:211], v169 offset:19456
	ds_read_b128 v[212:215], v169 offset:20480
	ds_read_b128 v[216:219], v169 offset:21504
	ds_read_b128 v[220:223], v169 offset:22528
	ds_read_b128 v[224:227], v169 offset:23552
	s_waitcnt vmcnt(8)
	s_waitcnt lgkmcnt(0)
	s_barrier
	s_waitcnt lgkmcnt(0)
	v_mfma_f32_16x16x32_bf16 v[60:63], v[128:131], v[196:199], v[60:63]
	v_mfma_f32_16x16x32_bf16 v[60:63], v[154:157], v[200:203], v[60:63]
	v_mfma_f32_16x16x32_bf16 v[56:59], v[176:179], v[200:203], v[56:59]
	v_mfma_f32_16x16x32_bf16 v[56:59], v[172:175], v[196:199], v[56:59]
	v_mfma_f32_16x16x32_bf16 v[52:55], v[180:183], v[196:199], v[52:55]
	v_mfma_f32_16x16x32_bf16 v[52:55], v[184:187], v[200:203], v[52:55]
	v_mfma_f32_16x16x32_bf16 v[48:51], v[192:195], v[200:203], v[48:51]
	v_mfma_f32_16x16x32_bf16 v[48:51], v[188:191], v[196:199], v[48:51]
	v_mfma_f32_16x16x32_bf16 v[32:35], v[188:191], v[204:207], v[32:35]
	v_mfma_f32_16x16x32_bf16 v[32:35], v[192:195], v[208:211], v[32:35]
	v_mfma_f32_16x16x32_bf16 v[36:39], v[184:187], v[208:211], v[36:39]
	v_mfma_f32_16x16x32_bf16 v[36:39], v[180:183], v[204:207], v[36:39]
	v_mfma_f32_16x16x32_bf16 v[40:43], v[172:175], v[204:207], v[40:43]
	v_mfma_f32_16x16x32_bf16 v[40:43], v[176:179], v[208:211], v[40:43]
	v_mfma_f32_16x16x32_bf16 v[44:47], v[154:157], v[208:211], v[44:47]
	v_mfma_f32_16x16x32_bf16 v[44:47], v[128:131], v[204:207], v[44:47]
	v_mfma_f32_16x16x32_bf16 v[28:31], v[128:131], v[212:215], v[28:31]
	v_mfma_f32_16x16x32_bf16 v[28:31], v[154:157], v[216:219], v[28:31]
	v_mfma_f32_16x16x32_bf16 v[24:27], v[176:179], v[216:219], v[24:27]
	v_mfma_f32_16x16x32_bf16 v[24:27], v[172:175], v[212:215], v[24:27]
	v_mfma_f32_16x16x32_bf16 v[20:23], v[180:183], v[212:215], v[20:23]
	v_mfma_f32_16x16x32_bf16 v[20:23], v[184:187], v[216:219], v[20:23]
	v_mfma_f32_16x16x32_bf16 v[16:19], v[192:195], v[216:219], v[16:19]
	v_mfma_f32_16x16x32_bf16 v[16:19], v[188:191], v[212:215], v[16:19]
	v_mfma_f32_16x16x32_bf16 v[0:3], v[188:191], v[220:223], v[0:3]
	v_mfma_f32_16x16x32_bf16 v[0:3], v[192:195], v[224:227], v[0:3]
	v_mfma_f32_16x16x32_bf16 v[4:7], v[184:187], v[224:227], v[4:7]
	v_mfma_f32_16x16x32_bf16 v[4:7], v[180:183], v[220:223], v[4:7]
	v_mfma_f32_16x16x32_bf16 v[8:11], v[172:175], v[220:223], v[8:11]
	v_mfma_f32_16x16x32_bf16 v[8:11], v[176:179], v[224:227], v[8:11]
	v_mfma_f32_16x16x32_bf16 v[12:15], v[154:157], v[224:227], v[12:15]
	v_mfma_f32_16x16x32_bf16 v[12:15], v[128:131], v[220:223], v[12:15]
	s_barrier
	s_add_i32 s55, 0, 0x18000
	v_add_u32_e32 v153, s55, v159
	s_add_i32 s56, 0, 0x1c000
	ds_read_b128 v[128:131], v153
	ds_read_b128 v[154:157], v153 offset:1024
	ds_read_b128 v[172:175], v153 offset:2048
	ds_read_b128 v[176:179], v153 offset:3072
	v_add_u32_e32 v153, s56, v159
	ds_read_b128 v[180:183], v153
	ds_read_b128 v[184:187], v153 offset:1024
	ds_read_b128 v[188:191], v153 offset:2048
	ds_read_b128 v[192:195], v153 offset:3072
	s_add_u32 s20, s26, 0x100000
	s_addc_u32 s21, s27, 0
	s_mov_b32 m0, s37
	v_lshl_add_u64 v[196:197], s[20:21], 0, v[132:133]
	global_load_lds_dwordx4 v[196:197], off
	v_lshl_add_u64 v[196:197], s[20:21], 0, v[136:137]
	s_mov_b32 m0, s38
	s_nop 0
	global_load_lds_dwordx4 v[196:197], off
	ds_read_b128 v[196:199], v169 offset:32768
	ds_read_b128 v[200:203], v169 offset:33792
	ds_read_b128 v[204:207], v169 offset:34816
	ds_read_b128 v[208:211], v169 offset:35840
	ds_read_b128 v[212:215], v169 offset:36864
	ds_read_b128 v[216:219], v169 offset:37888
	ds_read_b128 v[220:223], v169 offset:38912
	ds_read_b128 v[224:227], v169 offset:39936
	s_waitcnt vmcnt(8)
	s_waitcnt lgkmcnt(0)
	s_barrier
	s_waitcnt lgkmcnt(0)
	v_mfma_f32_16x16x32_bf16 v[124:127], v[128:131], v[196:199], v[124:127]
	v_mfma_f32_16x16x32_bf16 v[124:127], v[154:157], v[200:203], v[124:127]
	v_mfma_f32_16x16x32_bf16 v[120:123], v[176:179], v[200:203], v[120:123]
	v_mfma_f32_16x16x32_bf16 v[120:123], v[172:175], v[196:199], v[120:123]
	v_mfma_f32_16x16x32_bf16 v[116:119], v[180:183], v[196:199], v[116:119]
	v_mfma_f32_16x16x32_bf16 v[116:119], v[184:187], v[200:203], v[116:119]
	v_mfma_f32_16x16x32_bf16 v[112:115], v[192:195], v[200:203], v[112:115]
	v_mfma_f32_16x16x32_bf16 v[112:115], v[188:191], v[196:199], v[112:115]
	v_mfma_f32_16x16x32_bf16 v[96:99], v[188:191], v[204:207], v[96:99]
	v_mfma_f32_16x16x32_bf16 v[96:99], v[192:195], v[208:211], v[96:99]
	v_mfma_f32_16x16x32_bf16 v[100:103], v[184:187], v[208:211], v[100:103]
	v_mfma_f32_16x16x32_bf16 v[100:103], v[180:183], v[204:207], v[100:103]
	v_mfma_f32_16x16x32_bf16 v[104:107], v[172:175], v[204:207], v[104:107]
	v_mfma_f32_16x16x32_bf16 v[104:107], v[176:179], v[208:211], v[104:107]
	v_mfma_f32_16x16x32_bf16 v[108:111], v[154:157], v[208:211], v[108:111]
	v_mfma_f32_16x16x32_bf16 v[108:111], v[128:131], v[204:207], v[108:111]
	v_mfma_f32_16x16x32_bf16 v[92:95], v[128:131], v[212:215], v[92:95]
	v_mfma_f32_16x16x32_bf16 v[92:95], v[154:157], v[216:219], v[92:95]
	v_mfma_f32_16x16x32_bf16 v[88:91], v[176:179], v[216:219], v[88:91]
	v_mfma_f32_16x16x32_bf16 v[88:91], v[172:175], v[212:215], v[88:91]
	v_mfma_f32_16x16x32_bf16 v[84:87], v[180:183], v[212:215], v[84:87]
	v_mfma_f32_16x16x32_bf16 v[84:87], v[184:187], v[216:219], v[84:87]
	v_mfma_f32_16x16x32_bf16 v[80:83], v[192:195], v[216:219], v[80:83]
	v_mfma_f32_16x16x32_bf16 v[80:83], v[188:191], v[212:215], v[80:83]
	v_mfma_f32_16x16x32_bf16 v[64:67], v[188:191], v[220:223], v[64:67]
	v_mfma_f32_16x16x32_bf16 v[64:67], v[192:195], v[224:227], v[64:67]
	v_mfma_f32_16x16x32_bf16 v[68:71], v[184:187], v[224:227], v[68:71]
	v_mfma_f32_16x16x32_bf16 v[68:71], v[180:183], v[220:223], v[68:71]
	v_mfma_f32_16x16x32_bf16 v[72:75], v[172:175], v[220:223], v[72:75]
	v_mfma_f32_16x16x32_bf16 v[72:75], v[176:179], v[224:227], v[72:75]
	v_mfma_f32_16x16x32_bf16 v[76:79], v[154:157], v[224:227], v[76:79]
	v_mfma_f32_16x16x32_bf16 v[76:79], v[128:131], v[220:223], v[76:79]
	s_barrier
	s_add_i32 s20, s55, s30
	v_lshl_add_u64 v[160:161], v[160:161], 0, s[8:9]
	s_mov_b32 m0, s20
	s_nop 0
	global_load_lds_dwordx4 v[160:161], off
	s_add_i32 m0, s20, 0x2000
	s_add_u32 s20, s24, 0x100800
	v_lshl_add_u64 v[160:161], v[164:165], 0, s[8:9]
	s_addc_u32 s21, s25, 0
	s_add_i32 s24, s56, s30
	global_load_lds_dwordx4 v[160:161], off
	v_lshl_add_u64 v[160:161], s[20:21], 0, v[134:135]
	s_mov_b32 m0, s24
	s_nop 0
	global_load_lds_dwordx4 v[160:161], off
	v_lshl_add_u64 v[160:161], s[20:21], 0, v[138:139]
	s_add_i32 m0, s24, 0x2000
	s_nop 0
	global_load_lds_dwordx4 v[160:161], off
	v_lshl_add_u64 v[160:161], v[228:229], 0, s[8:9]
	s_mov_b32 m0, s41
	s_nop 0
	global_load_lds_dwordx4 v[160:161], off
	v_lshl_add_u64 v[160:161], v[230:231], 0, s[8:9]
	s_mov_b32 m0, s42
	s_nop 0
	global_load_lds_dwordx4 v[160:161], off
	ds_read_b128 v[196:199], v169 offset:49152
	ds_read_b128 v[200:203], v169 offset:50176
	ds_read_b128 v[204:207], v169 offset:51200
	ds_read_b128 v[208:211], v169 offset:52224
	ds_read_b128 v[212:215], v169 offset:53248
	ds_read_b128 v[216:219], v169 offset:54272
	ds_read_b128 v[220:223], v169 offset:55296
	ds_read_b128 v[224:227], v169 offset:56320
	s_waitcnt vmcnt(8)
	s_waitcnt lgkmcnt(0)
	s_barrier
	s_waitcnt lgkmcnt(0)
	v_mfma_f32_16x16x32_bf16 v[60:63], v[128:131], v[196:199], v[60:63]
	v_mfma_f32_16x16x32_bf16 v[60:63], v[154:157], v[200:203], v[60:63]
	v_mfma_f32_16x16x32_bf16 v[56:59], v[176:179], v[200:203], v[56:59]
	v_mfma_f32_16x16x32_bf16 v[56:59], v[172:175], v[196:199], v[56:59]
	v_mfma_f32_16x16x32_bf16 v[52:55], v[180:183], v[196:199], v[52:55]
	v_mfma_f32_16x16x32_bf16 v[52:55], v[184:187], v[200:203], v[52:55]
	v_mfma_f32_16x16x32_bf16 v[48:51], v[192:195], v[200:203], v[48:51]
	v_mfma_f32_16x16x32_bf16 v[48:51], v[188:191], v[196:199], v[48:51]
	v_mfma_f32_16x16x32_bf16 v[32:35], v[188:191], v[204:207], v[32:35]
	v_mfma_f32_16x16x32_bf16 v[32:35], v[192:195], v[208:211], v[32:35]
	v_mfma_f32_16x16x32_bf16 v[36:39], v[184:187], v[208:211], v[36:39]
	v_mfma_f32_16x16x32_bf16 v[36:39], v[180:183], v[204:207], v[36:39]
	v_mfma_f32_16x16x32_bf16 v[40:43], v[172:175], v[204:207], v[40:43]
	v_mfma_f32_16x16x32_bf16 v[40:43], v[176:179], v[208:211], v[40:43]
	v_mfma_f32_16x16x32_bf16 v[44:47], v[154:157], v[208:211], v[44:47]
	v_mfma_f32_16x16x32_bf16 v[44:47], v[128:131], v[204:207], v[44:47]
	v_mfma_f32_16x16x32_bf16 v[28:31], v[128:131], v[212:215], v[28:31]
	v_mfma_f32_16x16x32_bf16 v[28:31], v[154:157], v[216:219], v[28:31]
	v_mfma_f32_16x16x32_bf16 v[24:27], v[176:179], v[216:219], v[24:27]
	v_mfma_f32_16x16x32_bf16 v[24:27], v[172:175], v[212:215], v[24:27]
	v_mfma_f32_16x16x32_bf16 v[20:23], v[180:183], v[212:215], v[20:23]
	v_mfma_f32_16x16x32_bf16 v[20:23], v[184:187], v[216:219], v[20:23]
	v_mfma_f32_16x16x32_bf16 v[16:19], v[192:195], v[216:219], v[16:19]
	v_mfma_f32_16x16x32_bf16 v[16:19], v[188:191], v[212:215], v[16:19]
	v_mfma_f32_16x16x32_bf16 v[0:3], v[188:191], v[220:223], v[0:3]
	v_mfma_f32_16x16x32_bf16 v[0:3], v[192:195], v[224:227], v[0:3]
	v_mfma_f32_16x16x32_bf16 v[4:7], v[184:187], v[224:227], v[4:7]
	v_mfma_f32_16x16x32_bf16 v[4:7], v[180:183], v[220:223], v[4:7]
	v_mfma_f32_16x16x32_bf16 v[8:11], v[172:175], v[220:223], v[8:11]
	v_mfma_f32_16x16x32_bf16 v[8:11], v[176:179], v[224:227], v[8:11]
	v_mfma_f32_16x16x32_bf16 v[12:15], v[154:157], v[224:227], v[12:15]
	v_mfma_f32_16x16x32_bf16 v[12:15], v[128:131], v[220:223], v[12:15]
	s_barrier
	s_add_i32 s54, s54, 2
	s_add_u32 s52, s52, 0x1000
	s_addc_u32 s53, s53, 0
	s_cmp_gt_u32 s54, 61
	s_mov_b64 s[20:21], s[22:23]
	s_cbranch_scc0 .LBB0_1543

.LBB0_1550:
	s_lshl_b32 s11, s18, 4
	s_and_b32 s11, s11, 0x1f0
	s_or_b32 s22, s11, s43
	s_lshl_b32 s11, s49, 3
	s_or_b32 s20, s11, s40
	s_ashr_i32 s21, s20, 31
	s_cmp_lt_i32 s18, 32
	s_cselect_b32 s11, s47, 0x30100000
	s_add_u32 s11, s0, s11
	s_addc_u32 s13, s1, 0
	s_lshl_b32 s18, s22, 9
	s_add_u32 s22, s18, s20
	s_addc_u32 s23, 0, s21
	s_lshl_b64 s[22:23], s[22:23], 10
	v_pk_mul_f32 v[120:121], v[120:121], v[164:165] op_sel_hi:[1,0]
	s_add_u32 s22, s11, s22
	v_pk_mul_f32 v[124:125], v[124:125], v[164:165] op_sel_hi:[1,0]
	v_pk_mul_f32 v[122:123], v[122:123], v[164:165] op_sel_hi:[1,0]
	v_max_f32_e32 v120, 0, v120
	s_addc_u32 s23, s13, s23
	v_pk_mul_f32 v[126:127], v[126:127], v[164:165] op_sel_hi:[1,0]
	v_mul_f32_e32 v129, v120, v120
	v_max_f32_e32 v120, 0, v125
	v_max_f32_e32 v121, 0, v121
	v_max_f32_e32 v122, 0, v122
	v_lshl_add_u64 v[172:173], s[22:23], 0, v[140:141]
	v_mov_b32_e32 v153, v141
	v_max_f32_e32 v124, 0, v124
	v_mul_f32_e32 v120, v120, v120
	v_mul_f32_e32 v125, v121, v121
	v_max_f32_e32 v121, 0, v126
	v_mul_f32_e32 v126, v122, v122
	v_max_f32_e32 v122, 0, v127
	v_max_f32_e32 v123, 0, v123
	v_pk_mul_f32 v[112:113], v[112:113], v[164:165] op_sel_hi:[1,0]
	v_lshl_add_u64 v[172:173], v[172:173], 0, v[152:153]
	v_mul_f32_e32 v124, v124, v124
	v_mul_f32_e32 v121, v121, v121
	v_mul_f32_e32 v122, v122, v122
	v_mul_f32_e32 v123, v123, v123
	v_cvt_pk_bf16_f32 v120, v124, v120
	v_pk_mul_f32 v[116:117], v[116:117], v[164:165] op_sel_hi:[1,0]
	v_pk_mul_f32 v[114:115], v[114:115], v[164:165] op_sel_hi:[1,0]
	v_max_f32_e32 v112, 0, v112
	s_or_b32 s22, s18, 0x200
	v_cvt_pk_bf16_f32 v121, v121, v122
	v_cvt_pk_bf16_f32 v122, v129, v125
	v_cvt_pk_bf16_f32 v123, v126, v123
	global_store_dwordx4 v[172:173], v[120:123], off
	v_pk_mul_f32 v[118:119], v[118:119], v[164:165] op_sel_hi:[1,0]
	v_max_f32_e32 v116, 0, v116
	v_mul_f32_e32 v120, v112, v112
	v_max_f32_e32 v112, 0, v117
	v_max_f32_e32 v113, 0, v113
	v_max_f32_e32 v114, 0, v114
	s_add_u32 s22, s22, s20
	v_mul_f32_e32 v116, v116, v116
	v_mul_f32_e32 v112, v112, v112
	v_mul_f32_e32 v117, v113, v113
	v_max_f32_e32 v113, 0, v118
	v_mul_f32_e32 v118, v114, v114
	v_max_f32_e32 v114, 0, v119
	s_addc_u32 s23, 0, s21
	v_mul_f32_e32 v113, v113, v113
	v_mul_f32_e32 v114, v114, v114
	v_max_f32_e32 v115, 0, v115
	v_cvt_pk_bf16_f32 v112, v116, v112
	v_add_co_u32_e32 v116, vcc, s48, v172
	s_lshl_b64 s[22:23], s[22:23], 10
	v_pk_mul_f32 v[104:105], v[104:105], v[162:163] op_sel_hi:[1,0]
	v_mul_f32_e32 v115, v115, v115
	v_cvt_pk_bf16_f32 v113, v113, v114
	v_cvt_pk_bf16_f32 v114, v120, v117
	v_addc_co_u32_e32 v117, vcc, 0, v173, vcc
	s_add_u32 s22, s11, s22
	v_pk_mul_f32 v[108:109], v[108:109], v[162:163] op_sel_hi:[1,0]
	v_pk_mul_f32 v[106:107], v[106:107], v[162:163] op_sel_hi:[1,0]
	v_max_f32_e32 v104, 0, v104
	v_cvt_pk_bf16_f32 v115, v118, v115
	global_store_dwordx4 v[116:117], v[112:115], off
	s_addc_u32 s23, s13, s23
	v_pk_mul_f32 v[110:111], v[110:111], v[162:163] op_sel_hi:[1,0]
	v_mul_f32_e32 v114, v104, v104
	v_max_f32_e32 v104, 0, v109
	v_max_f32_e32 v105, 0, v105
	v_max_f32_e32 v106, 0, v106
	v_lshl_add_u64 v[112:113], s[22:23], 0, v[140:141]
	v_max_f32_e32 v108, 0, v108
	v_mul_f32_e32 v104, v104, v104
	v_mul_f32_e32 v109, v105, v105
	v_max_f32_e32 v105, 0, v110
	v_mul_f32_e32 v110, v106, v106
	v_max_f32_e32 v106, 0, v111
	v_max_f32_e32 v107, 0, v107
	v_pk_mul_f32 v[96:97], v[96:97], v[162:163] op_sel_hi:[1,0]
	v_lshl_add_u64 v[112:113], v[112:113], 0, v[152:153]
	v_mul_f32_e32 v108, v108, v108
	v_mul_f32_e32 v105, v105, v105
	v_mul_f32_e32 v106, v106, v106
	v_mul_f32_e32 v107, v107, v107
	v_cvt_pk_bf16_f32 v104, v108, v104
	v_pk_mul_f32 v[100:101], v[100:101], v[162:163] op_sel_hi:[1,0]
	v_pk_mul_f32 v[98:99], v[98:99], v[162:163] op_sel_hi:[1,0]
	v_max_f32_e32 v96, 0, v96
	s_or_b32 s22, s18, 0x400
	v_cvt_pk_bf16_f32 v105, v105, v106
	v_cvt_pk_bf16_f32 v106, v114, v109
	v_cvt_pk_bf16_f32 v107, v110, v107
	global_store_dwordx4 v[112:113], v[104:107], off
	v_pk_mul_f32 v[102:103], v[102:103], v[162:163] op_sel_hi:[1,0]
	v_max_f32_e32 v100, 0, v100
	v_mul_f32_e32 v104, v96, v96
	v_max_f32_e32 v96, 0, v101
	v_max_f32_e32 v97, 0, v97
	v_max_f32_e32 v98, 0, v98
	s_add_u32 s22, s22, s20
	v_mul_f32_e32 v100, v100, v100
	v_mul_f32_e32 v96, v96, v96
	v_mul_f32_e32 v101, v97, v97
	v_max_f32_e32 v97, 0, v102
	v_mul_f32_e32 v102, v98, v98
	v_max_f32_e32 v98, 0, v103
	s_addc_u32 s23, 0, s21
	v_mul_f32_e32 v97, v97, v97
	v_mul_f32_e32 v98, v98, v98
	v_max_f32_e32 v99, 0, v99
	v_cvt_pk_bf16_f32 v96, v100, v96
	v_add_co_u32_e32 v100, vcc, s48, v112
	s_lshl_b64 s[22:23], s[22:23], 10
	v_pk_mul_f32 v[88:89], v[88:89], v[160:161] op_sel_hi:[1,0]
	v_mul_f32_e32 v99, v99, v99
	v_cvt_pk_bf16_f32 v97, v97, v98
	v_cvt_pk_bf16_f32 v98, v104, v101
	v_addc_co_u32_e32 v101, vcc, 0, v113, vcc
	s_add_u32 s22, s11, s22
	v_pk_mul_f32 v[92:93], v[92:93], v[160:161] op_sel_hi:[1,0]
	v_pk_mul_f32 v[90:91], v[90:91], v[160:161] op_sel_hi:[1,0]
	v_max_f32_e32 v88, 0, v88
	v_cvt_pk_bf16_f32 v99, v102, v99
	global_store_dwordx4 v[100:101], v[96:99], off
	s_addc_u32 s23, s13, s23
	v_pk_mul_f32 v[94:95], v[94:95], v[160:161] op_sel_hi:[1,0]
	v_mul_f32_e32 v98, v88, v88
	v_max_f32_e32 v88, 0, v93
	v_max_f32_e32 v89, 0, v89
	v_max_f32_e32 v90, 0, v90
	v_lshl_add_u64 v[96:97], s[22:23], 0, v[140:141]
	v_max_f32_e32 v92, 0, v92
	v_mul_f32_e32 v88, v88, v88
	v_mul_f32_e32 v93, v89, v89
	v_max_f32_e32 v89, 0, v94
	v_mul_f32_e32 v94, v90, v90
	v_max_f32_e32 v90, 0, v95
	v_max_f32_e32 v91, 0, v91
	v_pk_mul_f32 v[80:81], v[80:81], v[160:161] op_sel_hi:[1,0]
	v_lshl_add_u64 v[96:97], v[96:97], 0, v[152:153]
	v_mul_f32_e32 v92, v92, v92
	v_mul_f32_e32 v89, v89, v89
	v_mul_f32_e32 v90, v90, v90
	v_mul_f32_e32 v91, v91, v91
	v_cvt_pk_bf16_f32 v88, v92, v88
	v_pk_mul_f32 v[84:85], v[84:85], v[160:161] op_sel_hi:[1,0]
	v_pk_mul_f32 v[82:83], v[82:83], v[160:161] op_sel_hi:[1,0]
	v_max_f32_e32 v80, 0, v80
	s_or_b32 s22, s18, 0x600
	v_cvt_pk_bf16_f32 v89, v89, v90
	v_cvt_pk_bf16_f32 v90, v98, v93
	v_cvt_pk_bf16_f32 v91, v94, v91
	global_store_dwordx4 v[96:97], v[88:91], off
	s_and_b64 vcc, exec, s[4:5]
	s_cbranch_vccz .Lepibar_P8
	s_barrier
.Lepibar_P8:
	v_pk_mul_f32 v[86:87], v[86:87], v[160:161] op_sel_hi:[1,0]
	v_max_f32_e32 v84, 0, v84
	v_mul_f32_e32 v88, v80, v80
	v_max_f32_e32 v80, 0, v85
	v_max_f32_e32 v81, 0, v81
	v_max_f32_e32 v82, 0, v82
	s_add_u32 s22, s22, s20
	v_mul_f32_e32 v84, v84, v84
	v_mul_f32_e32 v80, v80, v80
	v_mul_f32_e32 v85, v81, v81
	v_max_f32_e32 v81, 0, v86
	v_mul_f32_e32 v86, v82, v82
	v_max_f32_e32 v82, 0, v87
	s_addc_u32 s23, 0, s21
	v_mul_f32_e32 v81, v81, v81
	v_mul_f32_e32 v82, v82, v82
	v_max_f32_e32 v83, 0, v83
	v_cvt_pk_bf16_f32 v80, v84, v80
	v_add_co_u32_e32 v84, vcc, s48, v96
	s_lshl_b64 s[22:23], s[22:23], 10
	v_pk_mul_f32 v[72:73], v[72:73], v[158:159] op_sel_hi:[1,0]
	v_mul_f32_e32 v83, v83, v83
	v_cvt_pk_bf16_f32 v81, v81, v82
	v_cvt_pk_bf16_f32 v82, v88, v85
	v_addc_co_u32_e32 v85, vcc, 0, v97, vcc
	s_add_u32 s22, s11, s22
	v_pk_mul_f32 v[76:77], v[76:77], v[158:159] op_sel_hi:[1,0]
	v_pk_mul_f32 v[74:75], v[74:75], v[158:159] op_sel_hi:[1,0]
	v_max_f32_e32 v72, 0, v72
	v_cvt_pk_bf16_f32 v83, v86, v83
	global_store_dwordx4 v[84:85], v[80:83], off
	s_addc_u32 s23, s13, s23
	v_pk_mul_f32 v[78:79], v[78:79], v[158:159] op_sel_hi:[1,0]
	v_mul_f32_e32 v82, v72, v72
	v_max_f32_e32 v72, 0, v77
	v_max_f32_e32 v73, 0, v73
	v_max_f32_e32 v74, 0, v74
	v_lshl_add_u64 v[80:81], s[22:23], 0, v[140:141]
	v_max_f32_e32 v76, 0, v76
	v_mul_f32_e32 v72, v72, v72
	v_mul_f32_e32 v77, v73, v73
	v_max_f32_e32 v73, 0, v78
	v_mul_f32_e32 v78, v74, v74
	v_max_f32_e32 v74, 0, v79
	v_max_f32_e32 v75, 0, v75
	v_pk_mul_f32 v[64:65], v[64:65], v[158:159] op_sel_hi:[1,0]
	v_lshl_add_u64 v[80:81], v[80:81], 0, v[152:153]
	v_mul_f32_e32 v76, v76, v76
	v_mul_f32_e32 v73, v73, v73
	v_mul_f32_e32 v74, v74, v74
	v_mul_f32_e32 v75, v75, v75
	v_cvt_pk_bf16_f32 v72, v76, v72
	v_pk_mul_f32 v[68:69], v[68:69], v[158:159] op_sel_hi:[1,0]
	v_pk_mul_f32 v[66:67], v[66:67], v[158:159] op_sel_hi:[1,0]
	v_max_f32_e32 v64, 0, v64
	s_or_b32 s22, s18, 0x1000
	v_cvt_pk_bf16_f32 v73, v73, v74
	v_cvt_pk_bf16_f32 v74, v82, v77
	v_cvt_pk_bf16_f32 v75, v78, v75
	global_store_dwordx4 v[80:81], v[72:75], off
	v_pk_mul_f32 v[70:71], v[70:71], v[158:159] op_sel_hi:[1,0]
	v_max_f32_e32 v68, 0, v68
	v_mul_f32_e32 v72, v64, v64
	v_max_f32_e32 v64, 0, v69
	v_max_f32_e32 v65, 0, v65
	v_max_f32_e32 v66, 0, v66
	s_add_u32 s22, s22, s20
	v_mul_f32_e32 v68, v68, v68
	v_mul_f32_e32 v64, v64, v64
	v_mul_f32_e32 v69, v65, v65
	v_max_f32_e32 v65, 0, v70
	v_mul_f32_e32 v70, v66, v66
	v_max_f32_e32 v66, 0, v71
	s_addc_u32 s23, 0, s21
	v_mul_f32_e32 v65, v65, v65
	v_mul_f32_e32 v66, v66, v66
	v_max_f32_e32 v67, 0, v67
	v_cvt_pk_bf16_f32 v64, v68, v64
	v_add_co_u32_e32 v68, vcc, s48, v80
	s_lshl_b64 s[22:23], s[22:23], 10
	v_pk_mul_f32 v[56:57], v[56:57], v[156:157] op_sel_hi:[1,0]
	v_mul_f32_e32 v67, v67, v67
	v_cvt_pk_bf16_f32 v65, v65, v66
	v_cvt_pk_bf16_f32 v66, v72, v69
	v_addc_co_u32_e32 v69, vcc, 0, v81, vcc
	s_add_u32 s22, s11, s22
	v_pk_mul_f32 v[60:61], v[60:61], v[156:157] op_sel_hi:[1,0]
	v_pk_mul_f32 v[58:59], v[58:59], v[156:157] op_sel_hi:[1,0]
	v_max_f32_e32 v56, 0, v56
	v_cvt_pk_bf16_f32 v67, v70, v67
	global_store_dwordx4 v[68:69], v[64:67], off
	s_addc_u32 s23, s13, s23
	v_pk_mul_f32 v[62:63], v[62:63], v[156:157] op_sel_hi:[1,0]
	v_mul_f32_e32 v66, v56, v56
	v_max_f32_e32 v56, 0, v61
	v_max_f32_e32 v57, 0, v57
	v_max_f32_e32 v58, 0, v58
	v_lshl_add_u64 v[64:65], s[22:23], 0, v[140:141]
	v_max_f32_e32 v60, 0, v60
	v_mul_f32_e32 v56, v56, v56
	v_mul_f32_e32 v61, v57, v57
	v_max_f32_e32 v57, 0, v62
	v_mul_f32_e32 v62, v58, v58
	v_max_f32_e32 v58, 0, v63
	v_max_f32_e32 v59, 0, v59
	v_pk_mul_f32 v[48:49], v[48:49], v[156:157] op_sel_hi:[1,0]
	v_lshl_add_u64 v[64:65], v[64:65], 0, v[152:153]
	v_mul_f32_e32 v60, v60, v60
	v_mul_f32_e32 v57, v57, v57
	v_mul_f32_e32 v58, v58, v58
	v_mul_f32_e32 v59, v59, v59
	v_cvt_pk_bf16_f32 v56, v60, v56
	v_pk_mul_f32 v[52:53], v[52:53], v[156:157] op_sel_hi:[1,0]
	v_pk_mul_f32 v[50:51], v[50:51], v[156:157] op_sel_hi:[1,0]
	v_max_f32_e32 v48, 0, v48
	s_or_b32 s22, s18, 0x1200
	v_cvt_pk_bf16_f32 v57, v57, v58
	v_cvt_pk_bf16_f32 v58, v66, v61
	v_cvt_pk_bf16_f32 v59, v62, v59
	global_store_dwordx4 v[64:65], v[56:59], off
	v_pk_mul_f32 v[54:55], v[54:55], v[156:157] op_sel_hi:[1,0]
	v_max_f32_e32 v52, 0, v52
	v_mul_f32_e32 v56, v48, v48
	v_max_f32_e32 v48, 0, v53
	v_max_f32_e32 v49, 0, v49
	v_max_f32_e32 v50, 0, v50
	s_add_u32 s22, s22, s20
	v_mul_f32_e32 v52, v52, v52
	v_mul_f32_e32 v48, v48, v48
	v_mul_f32_e32 v53, v49, v49
	v_max_f32_e32 v49, 0, v54
	v_mul_f32_e32 v54, v50, v50
	v_max_f32_e32 v50, 0, v55
	s_addc_u32 s23, 0, s21
	v_mul_f32_e32 v49, v49, v49
	v_mul_f32_e32 v50, v50, v50
	v_max_f32_e32 v51, 0, v51
	v_cvt_pk_bf16_f32 v48, v52, v48
	v_add_co_u32_e32 v52, vcc, s48, v64
	s_lshl_b64 s[22:23], s[22:23], 10
	v_pk_mul_f32 v[40:41], v[40:41], v[154:155] op_sel_hi:[1,0]
	v_mul_f32_e32 v51, v51, v51
	v_cvt_pk_bf16_f32 v49, v49, v50
	v_cvt_pk_bf16_f32 v50, v56, v53
	v_addc_co_u32_e32 v53, vcc, 0, v65, vcc
	s_add_u32 s22, s11, s22
	v_pk_mul_f32 v[44:45], v[44:45], v[154:155] op_sel_hi:[1,0]
	v_pk_mul_f32 v[42:43], v[42:43], v[154:155] op_sel_hi:[1,0]
	v_max_f32_e32 v40, 0, v40
	v_cvt_pk_bf16_f32 v51, v54, v51
	global_store_dwordx4 v[52:53], v[48:51], off
	s_addc_u32 s23, s13, s23
	v_pk_mul_f32 v[46:47], v[46:47], v[154:155] op_sel_hi:[1,0]
	v_mul_f32_e32 v50, v40, v40
	v_max_f32_e32 v40, 0, v45
	v_max_f32_e32 v41, 0, v41
	v_max_f32_e32 v42, 0, v42
	v_lshl_add_u64 v[48:49], s[22:23], 0, v[140:141]
	v_max_f32_e32 v44, 0, v44
	v_mul_f32_e32 v40, v40, v40
	v_mul_f32_e32 v45, v41, v41
	v_max_f32_e32 v41, 0, v46
	v_mul_f32_e32 v46, v42, v42
	v_max_f32_e32 v42, 0, v47
	v_max_f32_e32 v43, 0, v43
	v_pk_mul_f32 v[32:33], v[32:33], v[154:155] op_sel_hi:[1,0]
	v_lshl_add_u64 v[48:49], v[48:49], 0, v[152:153]
	v_mul_f32_e32 v44, v44, v44
	v_mul_f32_e32 v41, v41, v41
	v_mul_f32_e32 v42, v42, v42
	v_mul_f32_e32 v43, v43, v43
	v_cvt_pk_bf16_f32 v40, v44, v40
	v_pk_mul_f32 v[36:37], v[36:37], v[154:155] op_sel_hi:[1,0]
	v_pk_mul_f32 v[34:35], v[34:35], v[154:155] op_sel_hi:[1,0]
	v_max_f32_e32 v32, 0, v32
	s_or_b32 s22, s18, 0x1400
	v_cvt_pk_bf16_f32 v41, v41, v42
	v_cvt_pk_bf16_f32 v42, v50, v45
	v_cvt_pk_bf16_f32 v43, v46, v43
	global_store_dwordx4 v[48:49], v[40:43], off
	v_pk_mul_f32 v[38:39], v[38:39], v[154:155] op_sel_hi:[1,0]
	v_max_f32_e32 v36, 0, v36
	v_mul_f32_e32 v40, v32, v32
	v_max_f32_e32 v32, 0, v37
	v_max_f32_e32 v33, 0, v33
	v_max_f32_e32 v34, 0, v34
	s_add_u32 s22, s22, s20
	v_mul_f32_e32 v36, v36, v36
	v_mul_f32_e32 v32, v32, v32
	v_mul_f32_e32 v37, v33, v33
	v_max_f32_e32 v33, 0, v38
	v_mul_f32_e32 v38, v34, v34
	v_max_f32_e32 v34, 0, v39
	s_addc_u32 s23, 0, s21
	v_mul_f32_e32 v33, v33, v33
	v_mul_f32_e32 v34, v34, v34
	v_max_f32_e32 v35, 0, v35
	v_cvt_pk_bf16_f32 v32, v36, v32
	v_add_co_u32_e32 v36, vcc, s48, v48
	s_lshl_b64 s[22:23], s[22:23], 10
	v_pk_mul_f32 v[24:25], v[24:25], v[130:131] op_sel_hi:[1,0]
	v_mul_f32_e32 v35, v35, v35
	v_cvt_pk_bf16_f32 v33, v33, v34
	v_cvt_pk_bf16_f32 v34, v40, v37
	v_addc_co_u32_e32 v37, vcc, 0, v49, vcc
	s_add_u32 s22, s11, s22
	v_pk_mul_f32 v[28:29], v[28:29], v[130:131] op_sel_hi:[1,0]
	v_pk_mul_f32 v[26:27], v[26:27], v[130:131] op_sel_hi:[1,0]
	v_max_f32_e32 v24, 0, v24
	v_cvt_pk_bf16_f32 v35, v38, v35
	global_store_dwordx4 v[36:37], v[32:35], off
	s_addc_u32 s23, s13, s23
	v_pk_mul_f32 v[30:31], v[30:31], v[130:131] op_sel_hi:[1,0]
	v_mul_f32_e32 v34, v24, v24
	v_max_f32_e32 v24, 0, v29
	v_max_f32_e32 v25, 0, v25
	v_max_f32_e32 v26, 0, v26
	v_lshl_add_u64 v[32:33], s[22:23], 0, v[140:141]
	v_max_f32_e32 v28, 0, v28
	v_mul_f32_e32 v24, v24, v24
	v_mul_f32_e32 v29, v25, v25
	v_max_f32_e32 v25, 0, v30
	v_mul_f32_e32 v30, v26, v26
	v_max_f32_e32 v26, 0, v31
	v_max_f32_e32 v27, 0, v27
	v_pk_mul_f32 v[16:17], v[16:17], v[130:131] op_sel_hi:[1,0]
	v_lshl_add_u64 v[32:33], v[32:33], 0, v[152:153]
	v_mul_f32_e32 v28, v28, v28
	v_mul_f32_e32 v25, v25, v25
	v_mul_f32_e32 v26, v26, v26
	v_mul_f32_e32 v27, v27, v27
	v_cvt_pk_bf16_f32 v24, v28, v24
	v_pk_mul_f32 v[20:21], v[20:21], v[130:131] op_sel_hi:[1,0]
	v_pk_mul_f32 v[18:19], v[18:19], v[130:131] op_sel_hi:[1,0]
	v_max_f32_e32 v16, 0, v16
	s_or_b32 s18, s18, 0x1600
	v_cvt_pk_bf16_f32 v25, v25, v26
	v_cvt_pk_bf16_f32 v26, v34, v29
	v_cvt_pk_bf16_f32 v27, v30, v27
	global_store_dwordx4 v[32:33], v[24:27], off
	v_pk_mul_f32 v[22:23], v[22:23], v[130:131] op_sel_hi:[1,0]
	v_max_f32_e32 v20, 0, v20
	v_mul_f32_e32 v24, v16, v16
	v_max_f32_e32 v16, 0, v21
	v_max_f32_e32 v17, 0, v17
	v_max_f32_e32 v18, 0, v18
	s_add_u32 s20, s18, s20
	v_mul_f32_e32 v20, v20, v20
	v_mul_f32_e32 v16, v16, v16
	v_mul_f32_e32 v21, v17, v17
	v_max_f32_e32 v17, 0, v22
	v_mul_f32_e32 v22, v18, v18
	v_max_f32_e32 v18, 0, v23
	s_addc_u32 s21, 0, s21
	v_mul_f32_e32 v17, v17, v17
	v_mul_f32_e32 v18, v18, v18
	v_max_f32_e32 v19, 0, v19
	v_cvt_pk_bf16_f32 v16, v20, v16
	v_add_co_u32_e32 v20, vcc, s48, v32
	s_lshl_b64 s[20:21], s[20:21], 10
	v_pk_mul_f32 v[8:9], v[8:9], v[128:129] op_sel_hi:[1,0]
	v_mul_f32_e32 v19, v19, v19
	v_cvt_pk_bf16_f32 v17, v17, v18
	v_cvt_pk_bf16_f32 v18, v24, v21
	v_addc_co_u32_e32 v21, vcc, 0, v33, vcc
	s_add_u32 s20, s11, s20
	v_pk_mul_f32 v[12:13], v[12:13], v[128:129] op_sel_hi:[1,0]
	v_pk_mul_f32 v[10:11], v[10:11], v[128:129] op_sel_hi:[1,0]
	v_max_f32_e32 v8, 0, v8
	v_cvt_pk_bf16_f32 v19, v22, v19
	global_store_dwordx4 v[20:21], v[16:19], off
	s_addc_u32 s21, s13, s21
	v_pk_mul_f32 v[14:15], v[14:15], v[128:129] op_sel_hi:[1,0]
	v_mul_f32_e32 v18, v8, v8
	v_max_f32_e32 v8, 0, v13
	v_max_f32_e32 v9, 0, v9
	v_max_f32_e32 v10, 0, v10
	v_lshl_add_u64 v[16:17], s[20:21], 0, v[140:141]
	v_max_f32_e32 v12, 0, v12
	v_mul_f32_e32 v8, v8, v8
	v_mul_f32_e32 v13, v9, v9
	v_max_f32_e32 v9, 0, v14
	v_mul_f32_e32 v14, v10, v10
	v_max_f32_e32 v10, 0, v15
	v_max_f32_e32 v11, 0, v11
	v_pk_mul_f32 v[0:1], v[0:1], v[128:129] op_sel_hi:[1,0]
	v_lshl_add_u64 v[16:17], v[16:17], 0, v[152:153]
	v_mul_f32_e32 v12, v12, v12
	v_mul_f32_e32 v9, v9, v9
	v_mul_f32_e32 v10, v10, v10
	v_mul_f32_e32 v11, v11, v11
	v_cvt_pk_bf16_f32 v8, v12, v8
	v_pk_mul_f32 v[4:5], v[4:5], v[128:129] op_sel_hi:[1,0]
	v_pk_mul_f32 v[2:3], v[2:3], v[128:129] op_sel_hi:[1,0]
	v_max_f32_e32 v0, 0, v0
	v_cvt_pk_bf16_f32 v9, v9, v10
	v_cvt_pk_bf16_f32 v10, v18, v13
	v_cvt_pk_bf16_f32 v11, v14, v11
	global_store_dwordx4 v[16:17], v[8:11], off
	v_pk_mul_f32 v[6:7], v[6:7], v[128:129] op_sel_hi:[1,0]
	v_max_f32_e32 v4, 0, v4
	v_mul_f32_e32 v8, v0, v0
	v_max_f32_e32 v0, 0, v5
	v_max_f32_e32 v1, 0, v1
	v_max_f32_e32 v2, 0, v2
	v_mul_f32_e32 v4, v4, v4
	v_mul_f32_e32 v0, v0, v0
	v_mul_f32_e32 v5, v1, v1
	v_max_f32_e32 v1, 0, v6
	v_mul_f32_e32 v6, v2, v2
	v_max_f32_e32 v2, 0, v7
	v_mul_f32_e32 v1, v1, v1
	v_mul_f32_e32 v2, v2, v2
	v_cvt_pk_bf16_f32 v0, v4, v0
	v_add_co_u32_e32 v4, vcc, 0x1000, v16
	v_max_f32_e32 v3, 0, v3
	v_cvt_pk_bf16_f32 v1, v1, v2
	v_cvt_pk_bf16_f32 v2, v8, v5
	s_nop 0
	v_addc_co_u32_e32 v5, vcc, 0, v17, vcc
	v_mul_f32_e32 v3, v3, v3
	s_andn2_b64 vcc, exec, s[2:3]
	s_mov_b64 s[2:3], -1
	v_cvt_pk_bf16_f32 v3, v6, v3
	global_store_dwordx4 v[4:5], v[0:3], off
	s_cbranch_vccnz .LBB0_1535
	s_andn2_b64 vcc, exec, s[6:7]
	s_cbranch_vccnz .LBB0_1534
	s_barrier
	s_branch .LBB0_1534

.LBB0_1625:
	ds_read_b128 v[128:131], v177
	ds_read_b128 v[132:135], v177 offset:1024
	ds_read_b128 v[136:139], v177 offset:2048
	ds_read_b128 v[140:143], v177 offset:3072
	ds_read_b128 v[144:147], v178
	ds_read_b128 v[148:151], v178 offset:1024
	ds_read_b128 v[170:173], v178 offset:2048
	ds_read_b128 v[182:185], v178 offset:3072
	s_add_u32 s24, s22, 0xffc00800
	s_addc_u32 s25, s23, -1
	s_cmpk_eq_i32 s57, 0xfc
	s_cselect_b32 s27, s29, s25
	s_cselect_b32 s26, s53, s24
	s_cselect_b32 s25, s17, s56
	s_cselect_b32 s24, s54, s55
	v_lshl_add_u64 v[186:187], s[22:23], 0, v[162:163]
	s_add_i32 m0, s38, 0xc000
	s_nop 0
	global_load_lds_dwordx4 v[186:187], off
	v_lshl_add_u64 v[186:187], s[22:23], 0, v[164:165]
	s_add_i32 m0, s38, 0xe000
	s_nop 0
	global_load_lds_dwordx4 v[186:187], off
	ds_read_b128 v[186:189], v179
	ds_read_b128 v[190:193], v179 offset:1024
	ds_read_b128 v[194:197], v179 offset:2048
	ds_read_b128 v[198:201], v179 offset:3072
	ds_read_b128 v[202:205], v179 offset:4096
	ds_read_b128 v[206:209], v179 offset:5120
	ds_read_b128 v[210:213], v179 offset:6144
	ds_read_b128 v[214:217], v179 offset:7168
	s_waitcnt vmcnt(8)
	s_waitcnt lgkmcnt(0)
	s_barrier
	s_waitcnt lgkmcnt(0)
	v_mfma_f32_16x16x32_bf16 v[124:127], v[128:131], v[186:189], v[124:127]
	v_mfma_f32_16x16x32_bf16 v[124:127], v[132:135], v[190:193], v[124:127]
	v_mfma_f32_16x16x32_bf16 v[120:123], v[140:143], v[190:193], v[120:123]
	v_mfma_f32_16x16x32_bf16 v[120:123], v[136:139], v[186:189], v[120:123]
	v_mfma_f32_16x16x32_bf16 v[116:119], v[144:147], v[186:189], v[116:119]
	v_mfma_f32_16x16x32_bf16 v[116:119], v[148:151], v[190:193], v[116:119]
	v_mfma_f32_16x16x32_bf16 v[112:115], v[182:185], v[190:193], v[112:115]
	v_mfma_f32_16x16x32_bf16 v[112:115], v[170:173], v[186:189], v[112:115]
	v_mfma_f32_16x16x32_bf16 v[96:99], v[170:173], v[194:197], v[96:99]
	v_mfma_f32_16x16x32_bf16 v[96:99], v[182:185], v[198:201], v[96:99]
	v_mfma_f32_16x16x32_bf16 v[100:103], v[148:151], v[198:201], v[100:103]
	v_mfma_f32_16x16x32_bf16 v[100:103], v[144:147], v[194:197], v[100:103]
	v_mfma_f32_16x16x32_bf16 v[104:107], v[136:139], v[194:197], v[104:107]
	v_mfma_f32_16x16x32_bf16 v[104:107], v[140:143], v[198:201], v[104:107]
	v_mfma_f32_16x16x32_bf16 v[108:111], v[132:135], v[198:201], v[108:111]
	v_mfma_f32_16x16x32_bf16 v[108:111], v[128:131], v[194:197], v[108:111]
	v_mfma_f32_16x16x32_bf16 v[92:95], v[128:131], v[202:205], v[92:95]
	v_mfma_f32_16x16x32_bf16 v[92:95], v[132:135], v[206:209], v[92:95]
	v_mfma_f32_16x16x32_bf16 v[88:91], v[140:143], v[206:209], v[88:91]
	v_mfma_f32_16x16x32_bf16 v[88:91], v[136:139], v[202:205], v[88:91]
	v_mfma_f32_16x16x32_bf16 v[84:87], v[144:147], v[202:205], v[84:87]
	v_mfma_f32_16x16x32_bf16 v[84:87], v[148:151], v[206:209], v[84:87]
	v_mfma_f32_16x16x32_bf16 v[80:83], v[182:185], v[206:209], v[80:83]
	v_mfma_f32_16x16x32_bf16 v[80:83], v[170:173], v[202:205], v[80:83]
	v_mfma_f32_16x16x32_bf16 v[64:67], v[170:173], v[210:213], v[64:67]
	v_mfma_f32_16x16x32_bf16 v[64:67], v[182:185], v[214:217], v[64:67]
	v_mfma_f32_16x16x32_bf16 v[68:71], v[148:151], v[214:217], v[68:71]
	v_mfma_f32_16x16x32_bf16 v[68:71], v[144:147], v[210:213], v[68:71]
	v_mfma_f32_16x16x32_bf16 v[72:75], v[136:139], v[210:213], v[72:75]
	v_mfma_f32_16x16x32_bf16 v[72:75], v[140:143], v[214:217], v[72:75]
	v_mfma_f32_16x16x32_bf16 v[76:79], v[132:135], v[214:217], v[76:79]
	v_mfma_f32_16x16x32_bf16 v[76:79], v[128:131], v[210:213], v[76:79]
	s_barrier
	s_add_i32 s58, s48, s37
	v_lshl_add_u64 v[218:219], s[24:25], 0, v[154:155]
	s_mov_b32 m0, s58
	v_lshl_add_u64 v[220:221], s[24:25], 0, v[158:159]
	global_load_lds_dwordx4 v[218:219], off
	s_add_i32 m0, s58, 0x2000
	s_add_u32 s58, s24, 0x400000
	s_addc_u32 s59, s25, 0
	s_add_i32 s60, s49, s37
	global_load_lds_dwordx4 v[220:221], off
	v_lshl_add_u64 v[186:187], s[58:59], 0, v[154:155]
	s_mov_b32 m0, s60
	v_lshl_add_u64 v[222:223], s[26:27], 0, v[152:153]
	global_load_lds_dwordx4 v[186:187], off
	v_lshl_add_u64 v[186:187], s[58:59], 0, v[158:159]
	s_add_i32 m0, s60, 0x2000
	v_lshl_add_u64 v[224:225], s[26:27], 0, v[156:157]
	global_load_lds_dwordx4 v[186:187], off
	s_mov_b32 m0, s38
	s_nop 0
	global_load_lds_dwordx4 v[222:223], off
	s_mov_b32 m0, s39
	s_nop 0
	global_load_lds_dwordx4 v[224:225], off
	ds_read_b128 v[186:189], v179 offset:16384
	ds_read_b128 v[190:193], v179 offset:17408
	ds_read_b128 v[194:197], v179 offset:18432
	ds_read_b128 v[198:201], v179 offset:19456
	ds_read_b128 v[202:205], v179 offset:20480
	ds_read_b128 v[206:209], v179 offset:21504
	ds_read_b128 v[210:213], v179 offset:22528
	ds_read_b128 v[214:217], v179 offset:23552
	s_waitcnt vmcnt(8)
	s_waitcnt lgkmcnt(0)
	s_barrier
	s_waitcnt lgkmcnt(0)
	v_mfma_f32_16x16x32_bf16 v[60:63], v[128:131], v[186:189], v[60:63]
	v_mfma_f32_16x16x32_bf16 v[60:63], v[132:135], v[190:193], v[60:63]
	v_mfma_f32_16x16x32_bf16 v[56:59], v[140:143], v[190:193], v[56:59]
	v_mfma_f32_16x16x32_bf16 v[56:59], v[136:139], v[186:189], v[56:59]
	v_mfma_f32_16x16x32_bf16 v[52:55], v[144:147], v[186:189], v[52:55]
	v_mfma_f32_16x16x32_bf16 v[52:55], v[148:151], v[190:193], v[52:55]
	v_mfma_f32_16x16x32_bf16 v[48:51], v[182:185], v[190:193], v[48:51]
	v_mfma_f32_16x16x32_bf16 v[48:51], v[170:173], v[186:189], v[48:51]
	v_mfma_f32_16x16x32_bf16 v[32:35], v[170:173], v[194:197], v[32:35]
	v_mfma_f32_16x16x32_bf16 v[32:35], v[182:185], v[198:201], v[32:35]
	v_mfma_f32_16x16x32_bf16 v[36:39], v[148:151], v[198:201], v[36:39]
	v_mfma_f32_16x16x32_bf16 v[36:39], v[144:147], v[194:197], v[36:39]
	v_mfma_f32_16x16x32_bf16 v[40:43], v[136:139], v[194:197], v[40:43]
	v_mfma_f32_16x16x32_bf16 v[40:43], v[140:143], v[198:201], v[40:43]
	v_mfma_f32_16x16x32_bf16 v[44:47], v[132:135], v[198:201], v[44:47]
	v_mfma_f32_16x16x32_bf16 v[44:47], v[128:131], v[194:197], v[44:47]
	v_mfma_f32_16x16x32_bf16 v[28:31], v[128:131], v[202:205], v[28:31]
	v_mfma_f32_16x16x32_bf16 v[28:31], v[132:135], v[206:209], v[28:31]
	v_mfma_f32_16x16x32_bf16 v[24:27], v[140:143], v[206:209], v[24:27]
	v_mfma_f32_16x16x32_bf16 v[24:27], v[136:139], v[202:205], v[24:27]
	v_mfma_f32_16x16x32_bf16 v[20:23], v[144:147], v[202:205], v[20:23]
	v_mfma_f32_16x16x32_bf16 v[20:23], v[148:151], v[206:209], v[20:23]
	v_mfma_f32_16x16x32_bf16 v[16:19], v[182:185], v[206:209], v[16:19]
	v_mfma_f32_16x16x32_bf16 v[16:19], v[170:173], v[202:205], v[16:19]
	v_mfma_f32_16x16x32_bf16 v[0:3], v[170:173], v[210:213], v[0:3]
	v_mfma_f32_16x16x32_bf16 v[0:3], v[182:185], v[214:217], v[0:3]
	v_mfma_f32_16x16x32_bf16 v[4:7], v[148:151], v[214:217], v[4:7]
	v_mfma_f32_16x16x32_bf16 v[4:7], v[144:147], v[210:213], v[4:7]
	v_mfma_f32_16x16x32_bf16 v[8:11], v[136:139], v[210:213], v[8:11]
	v_mfma_f32_16x16x32_bf16 v[8:11], v[140:143], v[214:217], v[8:11]
	v_mfma_f32_16x16x32_bf16 v[12:15], v[132:135], v[214:217], v[12:15]
	v_mfma_f32_16x16x32_bf16 v[12:15], v[128:131], v[210:213], v[12:15]
	s_barrier
	s_add_i32 s58, 0, 0x18000
	s_add_i32 s59, 0, 0x1c000
	v_add_u32_e32 v140, s58, v174
	v_add_u32_e32 v181, s59, v174
	ds_read_b128 v[128:131], v140
	ds_read_b128 v[132:135], v140 offset:1024
	ds_read_b128 v[136:139], v140 offset:2048
	ds_read_b128 v[140:143], v140 offset:3072
	ds_read_b128 v[144:147], v181
	ds_read_b128 v[148:151], v181 offset:1024
	ds_read_b128 v[170:173], v181 offset:2048
	ds_read_b128 v[182:185], v181 offset:3072
	s_add_u32 s26, s26, 0x400000
	s_addc_u32 s27, s27, 0
	s_mov_b32 m0, s40
	v_lshl_add_u64 v[186:187], s[26:27], 0, v[152:153]
	global_load_lds_dwordx4 v[186:187], off
	v_lshl_add_u64 v[186:187], s[26:27], 0, v[156:157]
	s_mov_b32 m0, s41
	s_nop 0
	global_load_lds_dwordx4 v[186:187], off
	ds_read_b128 v[186:189], v179 offset:32768
	ds_read_b128 v[190:193], v179 offset:33792
	ds_read_b128 v[194:197], v179 offset:34816
	ds_read_b128 v[198:201], v179 offset:35840
	ds_read_b128 v[202:205], v179 offset:36864
	ds_read_b128 v[206:209], v179 offset:37888
	ds_read_b128 v[210:213], v179 offset:38912
	ds_read_b128 v[214:217], v179 offset:39936
	s_waitcnt vmcnt(8)
	s_waitcnt lgkmcnt(0)
	s_barrier
	s_waitcnt lgkmcnt(0)
	v_mfma_f32_16x16x32_bf16 v[124:127], v[128:131], v[186:189], v[124:127]
	v_mfma_f32_16x16x32_bf16 v[124:127], v[132:135], v[190:193], v[124:127]
	v_mfma_f32_16x16x32_bf16 v[120:123], v[140:143], v[190:193], v[120:123]
	v_mfma_f32_16x16x32_bf16 v[120:123], v[136:139], v[186:189], v[120:123]
	v_mfma_f32_16x16x32_bf16 v[116:119], v[144:147], v[186:189], v[116:119]
	v_mfma_f32_16x16x32_bf16 v[116:119], v[148:151], v[190:193], v[116:119]
	v_mfma_f32_16x16x32_bf16 v[112:115], v[182:185], v[190:193], v[112:115]
	v_mfma_f32_16x16x32_bf16 v[112:115], v[170:173], v[186:189], v[112:115]
	v_mfma_f32_16x16x32_bf16 v[96:99], v[170:173], v[194:197], v[96:99]
	v_mfma_f32_16x16x32_bf16 v[96:99], v[182:185], v[198:201], v[96:99]
	v_mfma_f32_16x16x32_bf16 v[100:103], v[148:151], v[198:201], v[100:103]
	v_mfma_f32_16x16x32_bf16 v[100:103], v[144:147], v[194:197], v[100:103]
	v_mfma_f32_16x16x32_bf16 v[104:107], v[136:139], v[194:197], v[104:107]
	v_mfma_f32_16x16x32_bf16 v[104:107], v[140:143], v[198:201], v[104:107]
	v_mfma_f32_16x16x32_bf16 v[108:111], v[132:135], v[198:201], v[108:111]
	v_mfma_f32_16x16x32_bf16 v[108:111], v[128:131], v[194:197], v[108:111]
	v_mfma_f32_16x16x32_bf16 v[92:95], v[128:131], v[202:205], v[92:95]
	v_mfma_f32_16x16x32_bf16 v[92:95], v[132:135], v[206:209], v[92:95]
	v_mfma_f32_16x16x32_bf16 v[88:91], v[140:143], v[206:209], v[88:91]
	v_mfma_f32_16x16x32_bf16 v[88:91], v[136:139], v[202:205], v[88:91]
	v_mfma_f32_16x16x32_bf16 v[84:87], v[144:147], v[202:205], v[84:87]
	v_mfma_f32_16x16x32_bf16 v[84:87], v[148:151], v[206:209], v[84:87]
	v_mfma_f32_16x16x32_bf16 v[80:83], v[182:185], v[206:209], v[80:83]
	v_mfma_f32_16x16x32_bf16 v[80:83], v[170:173], v[202:205], v[80:83]
	v_mfma_f32_16x16x32_bf16 v[64:67], v[170:173], v[210:213], v[64:67]
	v_mfma_f32_16x16x32_bf16 v[64:67], v[182:185], v[214:217], v[64:67]
	v_mfma_f32_16x16x32_bf16 v[68:71], v[148:151], v[214:217], v[68:71]
	v_mfma_f32_16x16x32_bf16 v[68:71], v[144:147], v[210:213], v[68:71]
	v_mfma_f32_16x16x32_bf16 v[72:75], v[136:139], v[210:213], v[72:75]
	v_mfma_f32_16x16x32_bf16 v[72:75], v[140:143], v[214:217], v[72:75]
	v_mfma_f32_16x16x32_bf16 v[76:79], v[132:135], v[214:217], v[76:79]
	v_mfma_f32_16x16x32_bf16 v[76:79], v[128:131], v[210:213], v[76:79]
	s_barrier
	s_add_i32 s26, s58, s37
	v_lshl_add_u64 v[186:187], v[218:219], 0, s[14:15]
	s_mov_b32 m0, s26
	s_nop 0
	global_load_lds_dwordx4 v[186:187], off
	s_add_i32 m0, s26, 0x2000
	s_add_u32 s24, s24, 0x400800
	v_lshl_add_u64 v[186:187], v[220:221], 0, s[14:15]
	s_addc_u32 s25, s25, 0
	s_add_i32 s26, s59, s37
	global_load_lds_dwordx4 v[186:187], off
	v_lshl_add_u64 v[186:187], s[24:25], 0, v[154:155]
	s_mov_b32 m0, s26
	s_nop 0
	global_load_lds_dwordx4 v[186:187], off
	v_lshl_add_u64 v[186:187], s[24:25], 0, v[158:159]
	s_add_i32 m0, s26, 0x2000
	s_nop 0
	global_load_lds_dwordx4 v[186:187], off
	v_lshl_add_u64 v[186:187], v[222:223], 0, s[14:15]
	s_mov_b32 m0, s43
	s_nop 0
	global_load_lds_dwordx4 v[186:187], off
	v_lshl_add_u64 v[186:187], v[224:225], 0, s[14:15]
	s_mov_b32 m0, s44
	s_nop 0
	global_load_lds_dwordx4 v[186:187], off
	ds_read_b128 v[186:189], v179 offset:49152
	ds_read_b128 v[190:193], v179 offset:50176
	ds_read_b128 v[194:197], v179 offset:51200
	ds_read_b128 v[198:201], v179 offset:52224
	ds_read_b128 v[202:205], v179 offset:53248
	ds_read_b128 v[206:209], v179 offset:54272
	ds_read_b128 v[210:213], v179 offset:55296
	ds_read_b128 v[214:217], v179 offset:56320
	s_waitcnt vmcnt(8)
	s_waitcnt lgkmcnt(0)
	s_barrier
	s_waitcnt lgkmcnt(0)
	v_mfma_f32_16x16x32_bf16 v[60:63], v[128:131], v[186:189], v[60:63]
	v_mfma_f32_16x16x32_bf16 v[60:63], v[132:135], v[190:193], v[60:63]
	v_mfma_f32_16x16x32_bf16 v[56:59], v[140:143], v[190:193], v[56:59]
	v_mfma_f32_16x16x32_bf16 v[56:59], v[136:139], v[186:189], v[56:59]
	v_mfma_f32_16x16x32_bf16 v[52:55], v[144:147], v[186:189], v[52:55]
	v_mfma_f32_16x16x32_bf16 v[52:55], v[148:151], v[190:193], v[52:55]
	v_mfma_f32_16x16x32_bf16 v[48:51], v[182:185], v[190:193], v[48:51]
	v_mfma_f32_16x16x32_bf16 v[48:51], v[170:173], v[186:189], v[48:51]
	v_mfma_f32_16x16x32_bf16 v[32:35], v[170:173], v[194:197], v[32:35]
	v_mfma_f32_16x16x32_bf16 v[32:35], v[182:185], v[198:201], v[32:35]
	v_mfma_f32_16x16x32_bf16 v[36:39], v[148:151], v[198:201], v[36:39]
	v_mfma_f32_16x16x32_bf16 v[36:39], v[144:147], v[194:197], v[36:39]
	v_mfma_f32_16x16x32_bf16 v[40:43], v[136:139], v[194:197], v[40:43]
	v_mfma_f32_16x16x32_bf16 v[40:43], v[140:143], v[198:201], v[40:43]
	v_mfma_f32_16x16x32_bf16 v[44:47], v[132:135], v[198:201], v[44:47]
	v_mfma_f32_16x16x32_bf16 v[44:47], v[128:131], v[194:197], v[44:47]
	v_mfma_f32_16x16x32_bf16 v[28:31], v[128:131], v[202:205], v[28:31]
	v_mfma_f32_16x16x32_bf16 v[28:31], v[132:135], v[206:209], v[28:31]
	v_mfma_f32_16x16x32_bf16 v[24:27], v[140:143], v[206:209], v[24:27]
	v_mfma_f32_16x16x32_bf16 v[24:27], v[136:139], v[202:205], v[24:27]
	v_mfma_f32_16x16x32_bf16 v[20:23], v[144:147], v[202:205], v[20:23]
	v_mfma_f32_16x16x32_bf16 v[20:23], v[148:151], v[206:209], v[20:23]
	v_mfma_f32_16x16x32_bf16 v[16:19], v[182:185], v[206:209], v[16:19]
	v_mfma_f32_16x16x32_bf16 v[16:19], v[170:173], v[202:205], v[16:19]
	v_mfma_f32_16x16x32_bf16 v[0:3], v[170:173], v[210:213], v[0:3]
	v_mfma_f32_16x16x32_bf16 v[0:3], v[182:185], v[214:217], v[0:3]
	v_mfma_f32_16x16x32_bf16 v[4:7], v[148:151], v[214:217], v[4:7]
	v_mfma_f32_16x16x32_bf16 v[4:7], v[144:147], v[210:213], v[4:7]
	v_mfma_f32_16x16x32_bf16 v[8:11], v[136:139], v[210:213], v[8:11]
	v_mfma_f32_16x16x32_bf16 v[8:11], v[140:143], v[214:217], v[8:11]
	v_mfma_f32_16x16x32_bf16 v[12:15], v[132:135], v[214:217], v[12:15]
	v_mfma_f32_16x16x32_bf16 v[12:15], v[128:131], v[210:213], v[12:15]
	s_barrier
	s_add_i32 s57, s57, 2
	s_add_u32 s22, s22, 0x1000
	s_addc_u32 s23, s23, 0
	s_add_u32 s55, s55, 0x1000
	s_addc_u32 s56, s56, 0
	s_cmpk_gt_u32 s57, 0xfd
	s_cbranch_scc0 .LBB0_1625

.LBB0_1632:
	s_or_b64 exec, exec, s[28:29]
	s_and_b64 vcc, exec, s[6:7]
	s_cbranch_vccz .Lepibar_P9
	s_barrier
.Lepibar_P9:
	v_lshlrev_b32_e32 v98, 16, v140
	v_and_b32_e32 v99, 0xffff0000, v140
	v_lshlrev_b32_e32 v100, 16, v141
	v_and_b32_e32 v101, 0xffff0000, v141
	v_lshlrev_b32_e32 v102, 16, v142
	v_and_b32_e32 v103, 0xffff0000, v142
	v_lshlrev_b32_e32 v104, 16, v143
	v_and_b32_e32 v105, 0xffff0000, v143
	v_pk_add_f32 v[94:95], v[94:95], v[100:101]
	v_pk_add_f32 v[92:93], v[92:93], v[98:99]
	v_pk_add_f32 v[98:99], v[90:91], v[104:105]
	v_pk_add_f32 v[90:91], v[88:89], v[102:103]
	v_mul_f32_e32 v88, v93, v93
	v_mul_f32_e32 v89, v95, v95
	v_fmac_f32_e32 v88, v92, v92
	v_fmac_f32_e32 v89, v94, v94
	v_add_f32_e32 v88, v88, v89
	v_mul_f32_e32 v89, v91, v91
	v_mul_f32_e32 v100, v99, v99
	v_lshlrev_b32_e32 v106, 16, v136
	v_and_b32_e32 v107, 0xffff0000, v136
	v_lshlrev_b32_e32 v108, 16, v137
	v_and_b32_e32 v109, 0xffff0000, v137
	v_fmac_f32_e32 v89, v90, v90
	v_fmac_f32_e32 v100, v98, v98
	v_lshlrev_b32_e32 v110, 16, v138
	v_and_b32_e32 v111, 0xffff0000, v138
	v_add_f32_e32 v89, v89, v100
	v_pk_add_f32 v[86:87], v[86:87], v[108:109]
	v_pk_add_f32 v[84:85], v[84:85], v[106:107]
	v_lshlrev_b32_e32 v112, 16, v139
	v_and_b32_e32 v113, 0xffff0000, v139
	v_add_f32_e32 v100, v88, v89
	v_cvt_pk_bf16_f32 v88, v92, v93
	v_cvt_pk_bf16_f32 v89, v94, v95
	v_cvt_pk_bf16_f32 v90, v90, v91
	v_cvt_pk_bf16_f32 v91, v98, v99
	v_pk_add_f32 v[98:99], v[80:81], v[110:111]
	v_mul_f32_e32 v80, v85, v85
	v_mul_f32_e32 v81, v87, v87
	v_pk_add_f32 v[94:95], v[82:83], v[112:113]
	v_fmac_f32_e32 v80, v84, v84
	v_fmac_f32_e32 v81, v86, v86
	v_add_f32_e32 v80, v80, v81
	v_mul_f32_e32 v81, v99, v99
	v_mul_f32_e32 v82, v95, v95
	v_fmac_f32_e32 v81, v98, v98
	v_fmac_f32_e32 v82, v94, v94
	v_add_f32_e32 v81, v81, v82
	v_add_f32_e32 v80, v80, v81
	v_add_f32_e32 v83, v100, v80
	ds_bpermute_b32 v100, v114, v83
	v_or_b32_e32 v96, 32, v172
	s_waitcnt lgkmcnt(1)
	v_ashrrev_i32_e32 v97, 31, v96
	v_lshlrev_b64 v[92:93], 13, v[96:97]
	v_lshl_add_u64 v[80:81], s[10:11], 0, v[92:93]
	v_lshl_add_u64 v[92:93], v[170:171], 1, v[80:81]
	s_waitcnt lgkmcnt(0)
	v_add_f32_e32 v80, v83, v100
	ds_bpermute_b32 v81, v115, v80
	global_store_dwordx4 v[92:93], v[88:91], off
	v_cvt_pk_bf16_f32 v82, v84, v85
	v_cvt_pk_bf16_f32 v83, v86, v87
	v_cvt_pk_bf16_f32 v84, v98, v99
	v_cvt_pk_bf16_f32 v85, v94, v95
	global_store_dwordx4 v[92:93], v[82:85], off offset:256
	s_and_saveexec_b64 s[28:29], s[2:3]
	s_cbranch_execz .LBB0_1634
	v_lshlrev_b64 v[82:83], 8, v[96:97]
	v_lshl_add_u64 v[82:83], s[12:13], 0, v[82:83]
	v_lshl_add_u64 v[82:83], s[22:23], 2, v[82:83]
	s_lshl_b32 s0, s42, 2
	v_lshl_add_u64 v[82:83], v[82:83], 0, s[0:1]
	s_waitcnt lgkmcnt(0)
	v_add_f32_e32 v80, v80, v81
	global_store_dword v[82:83], v80, off
